# phase 1 and phase 5 bf16 row stores also widened to 16-byte stores through v_permlane16_swap
# speedup vs baseline: 1.0321x; 1.0133x over previous
; template <int AI>
; __device__ __forceinline__ void epi_inproj(const Params& p, const acc8_t& acc, int g, int tbase, int fr, int fq) {
;     ...
;   const bool sample = tbase >= NPROMPT;
;   int b, trow;
;   if (!sample) { b = tbase >> 13; trow = tbase & 8191; } else { b = (tbase - NPROMPT) >> 6; trow = 0; }
;   const float* gain = nullptr; bool rope = false, sig = false;
;   u16* bdst = nullptr; size_t brow0 = 0; int bld = 0, bcol = 0;
;   u16* vdst = nullptr; int vS = 0, vcol0 = 0;
;   float* fdst = nullptr; size_t frow0 = 0; int fld = 0, fcol = 0;
;   bool wi = false;
;   if (g < 8) { gain = p.in[9]; rope = true; bdst = (u16*)(ws + OFF_QA); brow0 = tbase; bld = 512; bcol = g * 64; }
;   else if (g < 16) {
;     int hd = g - 8; gain = p.in[10]; rope = true; bld = 64;
;     if (!sample) { bdst = (u16*)(ws + OFF_KAP) + (size_t)(b * 8 + hd) * 8192 * 64; brow0 = trow; fdst = p.out + O_KAP; frow0 = tbase; }
;     else { bdst = (u16*)(ws + OFF_KAS) + (size_t)(b * 8 + hd) * 1088 * 64; brow0 = 1024; fdst = p.out + O_KAS; frow0 = b * 64; }
;     fld = 512; fcol = hd * 64;
;   } else if (g < 24) {
;     int hd = g - 16;
;     if (!sample) { vdst = (u16*)(ws + OFF_VAP) + (size_t)(b * 8 + hd) * 64 * 8192; vS = 8192; vcol0 = trow; fdst = p.out + O_VAP; frow0 = tbase; }
;     else { vdst = (u16*)(ws + OFF_VAS) + (size_t)(b * 8 + hd) * 64 * 1088; vS = 1088; vcol0 = 1024; fdst = p.out + O_VAS; frow0 = b * 64; }
;     fld = 512; fcol = hd * 64;
;   } else if (g < 32) { rope = true; bdst = (u16*)(ws + OFF_QI); brow0 = tbase; bld = 512; bcol = (g - 24) * 64; }
;   else if (g == 32) {
;     gain = p.in[11]; rope = true; bld = 64; fld = 64;
;     if (!sample) { bdst = (u16*)(ws + OFF_KIP) + (size_t)b * 8192 * 64; brow0 = trow; fdst = p.out + O_KIP; frow0 = tbase; }
;     else { bdst = (u16*)(ws + OFF_KIS) + (size_t)b * 1088 * 64; brow0 = 1024; fdst = p.out + O_KIS; frow0 = b * 64; }
;   } else if (g < 41) { gain = p.in[12]; bdst = (u16*)(ws + OFF_QB); brow0 = tbase; bld = 512; bcol = (g - 33) * 64; }
;   else if (g < 49) {
;     int hd = g - 41; gain = p.in[13]; bld = 64; fld = 512; fcol = hd * 64;
;     if (!sample) {
;       bdst = (u16*)(ws + OFF_KBP) + (size_t)(b * 8 + hd) * 8192 * 64; brow0 = trow;
;       if (trow >= 7680) { fdst = p.out + O_KBP; frow0 = b * 512 + (trow - 7680); }
.LBB0_282:
	s_xor_b64 s[22:23], s[22:23], -1
	s_and_b64 s[4:5], s[4:5], exec
	s_cselect_b32 s1, 0x400, s64
	s_cmp_lg_u64 s[12:13], 0
	s_cselect_b64 s[96:97], -1, 0
	s_ashr_i32 s93, s92, 31
	s_lshl_b64 s[6:7], s[92:93], 1
	s_add_u32 s6, s12, s6
	s_addc_u32 s7, s13, s7
	s_cmp_lg_u64 s[18:19], 0
	v_and_b32_e32 v148, 4, v146
	s_cselect_b64 s[94:95], -1, 0
	s_lshr_b32 s64, s43, 6
	v_lshlrev_b32_e32 v154, 3, v148
	v_and_b32_e32 v148, 1, v160
	s_lshl_b64 s[12:13], s[64:65], 13
	v_cmp_eq_u32_e64 s[8:9], 0, v148
	v_and_b32_e32 v148, 2, v160
	s_add_u32 s12, s18, s12
	v_lshl_add_u64 v[166:167], v[146:147], 1, s[6:7]
	v_and_b32_e32 v206, 1, v192
	v_mov_b32_e32 v207, 0
	v_mul_u32_u24_e32 v206, 24, v206
	v_lshl_add_u64 v[166:167], v[166:167], 0, v[206:207]
	v_cmp_eq_u32_e64 s[6:7], 0, v148
	s_addc_u32 s13, s19, s13
	v_and_b32_e32 v148, -4, v160
	v_ashrrev_i32_e32 v149, 31, v148
	s_cmp_lg_u64 s[28:29], 0
	s_mov_b32 s43, s65
	v_lshl_add_u64 v[164:165], v[148:149], 1, s[12:13]
	s_cselect_b64 s[92:93], -1, 0
	s_lshl_b64 s[12:13], s[42:43], 2
	s_add_u32 s12, s28, s12
	s_addc_u32 s13, s29, s13
	v_lshlrev_b64 v[170:171], 2, v[146:147]
	v_cndmask_b32_e64 v146, 0, 1, s[10:11]
	v_lshl_add_u64 v[168:169], s[52:53], 0, v[154:155]
	v_cmp_gt_i32_e64 s[4:5], 2, v192
	v_lshl_add_u64 v[162:163], s[12:13], 0, v[170:171]
	s_mov_b64 s[12:13], -1
	s_and_b64 vcc, s[84:85], s[22:23]
	s_andn2_b64 vcc, exec, vcc
	s_cbranch_vccnz .Lp1cs_a_skip
	v_add_u32_e32 v210, s1, v160
	v_ashrrev_i32_e32 v211, 31, v210
	v_lshlrev_b64 v[210:211], 6, v[210:211]
	v_lshl_add_u64 v[210:211], v[168:169], 0, v[210:211]
	global_load_dwordx4 v[206:209], v[210:211], off offset:16
	s_nop 0
	global_load_dwordx4 v[210:213], v[210:211], off
	v_add3_u32 v218, s1, v160, 16
	v_ashrrev_i32_e32 v219, 31, v218
	v_lshlrev_b64 v[218:219], 6, v[218:219]
	v_lshl_add_u64 v[218:219], v[168:169], 0, v[218:219]
	global_load_dwordx4 v[214:217], v[218:219], off offset:16
	s_nop 0
	global_load_dwordx4 v[218:221], v[218:219], off
	v_add3_u32 v226, s1, v160, 32
	v_ashrrev_i32_e32 v227, 31, v226
	v_lshlrev_b64 v[226:227], 6, v[226:227]
	v_lshl_add_u64 v[226:227], v[168:169], 0, v[226:227]
	global_load_dwordx4 v[222:225], v[226:227], off offset:16
	s_nop 0
	global_load_dwordx4 v[226:229], v[226:227], off
	v_add3_u32 v234, s1, v160, 48
	v_ashrrev_i32_e32 v235, 31, v234
	v_lshlrev_b64 v[234:235], 6, v[234:235]
	v_lshl_add_u64 v[234:235], v[168:169], 0, v[234:235]
	global_load_dwordx4 v[230:233], v[234:235], off offset:16
	s_nop 0
	global_load_dwordx4 v[234:237], v[234:235], off

; template <int AI>
; __device__ __forceinline__ void epi_inproj(const Params& p, const acc8_t& acc, int g, int tbase, int fr, int fq) {
;     ...
;     if (bdst) {
;       u16* d = bdst + (brow0 + tl) * (size_t)bld + bcol;
; #pragma unroll
;       for (int bj = 0; bj < 2; bj++)
; #pragma unroll
;         for (int n = 0; n < 2; n++) {
;           uint2 o;
;           o.x = pack2(x[(bj * 2 + n) * 4 + 0], x[(bj * 2 + n) * 4 + 1]);
;           o.y = pack2(x[(bj * 2 + n) * 4 + 2], x[(bj * 2 + n) * 4 + 3]);
;           *(uint2*)(d + 32 * bj + 16 * n + 4 * fq) = o;
;         }
;     }
.LBB0_288:
	v_lshl_add_u64 v[194:195], s[38:39], 0, v[160:161]
	v_mul_lo_u32 v154, v195, s66
	v_mul_lo_u32 v193, v194, s67
	v_mad_u64_u32 v[194:195], s[12:13], v194, s66, 0
	v_add3_u32 v195, v195, v193, v154
	v_lshl_add_u64 v[194:195], v[194:195], 1, v[166:167]
	v_cvt_pk_bf16_f32 v206, v146, v147
	v_cvt_pk_bf16_f32 v207, v148, v149
	v_cvt_pk_bf16_f32 v208, v126, v127
	v_cvt_pk_bf16_f32 v209, v128, v129
	v_cvt_pk_bf16_f32 v210, v118, v119
	v_cvt_pk_bf16_f32 v211, v120, v121
	v_cvt_pk_bf16_f32 v212, v114, v115
	v_cvt_pk_bf16_f32 v213, v116, v117
	v_permlane16_swap_b32_e32 v206, v208
	v_permlane16_swap_b32_e32 v207, v209
	v_permlane16_swap_b32_e32 v210, v212
	v_permlane16_swap_b32_e32 v211, v213
	global_store_dwordx4 v[194:195], v[206:209], off
	global_store_dwordx4 v[194:195], v[210:213], off offset:64
	s_nop 1

; template <int AI>
; __device__ __forceinline__ void epi_inproj(const Params& p, const acc8_t& acc, int g, int tbase, int fr, int fq) {
;     ...
;     if (bdst) {
;       u16* d = bdst + (brow0 + tl) * (size_t)bld + bcol;
; #pragma unroll
;       for (int bj = 0; bj < 2; bj++)
; #pragma unroll
;         for (int n = 0; n < 2; n++) {
;           uint2 o;
;           o.x = pack2(x[(bj * 2 + n) * 4 + 0], x[(bj * 2 + n) * 4 + 1]);
;           o.y = pack2(x[(bj * 2 + n) * 4 + 2], x[(bj * 2 + n) * 4 + 3]);
;           *(uint2*)(d + 32 * bj + 16 * n + 4 * fq) = o;
;         }
;     }
.LBB0_309:
	v_lshl_add_u64 v[122:123], s[38:39], 0, v[120:121]
	v_mul_lo_u32 v124, v123, s66
	v_mul_lo_u32 v125, v122, s67
	v_mad_u64_u32 v[122:123], s[18:19], v122, s66, 0
	v_add3_u32 v123, v123, v125, v124
	v_lshl_add_u64 v[122:123], v[122:123], 1, v[166:167]
	v_cvt_pk_bf16_f32 v214, v114, v115
	v_cvt_pk_bf16_f32 v215, v116, v117
	v_cvt_pk_bf16_f32 v216, v110, v111
	v_cvt_pk_bf16_f32 v217, v112, v113
	v_cvt_pk_bf16_f32 v218, v102, v103
	v_cvt_pk_bf16_f32 v219, v104, v105
	v_cvt_pk_bf16_f32 v220, v98, v99
	v_cvt_pk_bf16_f32 v221, v100, v101
	v_permlane16_swap_b32_e32 v214, v216
	v_permlane16_swap_b32_e32 v215, v217
	v_permlane16_swap_b32_e32 v218, v220
	v_permlane16_swap_b32_e32 v219, v221
	global_store_dwordx4 v[122:123], v[214:217], off
	global_store_dwordx4 v[122:123], v[218:221], off offset:64
	s_nop 1

; template <int AI>
; __device__ __forceinline__ void epi_inproj(const Params& p, const acc8_t& acc, int g, int tbase, int fr, int fq) {
;     ...
;     if (bdst) {
;       u16* d = bdst + (brow0 + tl) * (size_t)bld + bcol;
; #pragma unroll
;       for (int bj = 0; bj < 2; bj++)
; #pragma unroll
;         for (int n = 0; n < 2; n++) {
;           uint2 o;
;           o.x = pack2(x[(bj * 2 + n) * 4 + 0], x[(bj * 2 + n) * 4 + 1]);
;           o.y = pack2(x[(bj * 2 + n) * 4 + 2], x[(bj * 2 + n) * 4 + 3]);
;           *(uint2*)(d + 32 * bj + 16 * n + 4 * fq) = o;
;         }
;     }
.LBB0_323:
	v_lshl_add_u64 v[104:105], s[38:39], 0, v[102:103]
	v_mul_lo_u32 v106, v105, s66
	v_mul_lo_u32 v107, v104, s67
	v_mad_u64_u32 v[104:105], s[18:19], v104, s66, 0
	v_add3_u32 v105, v105, v107, v106
	v_lshl_add_u64 v[104:105], v[104:105], 1, v[166:167]
	v_cvt_pk_bf16_f32 v222, v98, v99
	v_cvt_pk_bf16_f32 v223, v100, v101
	v_cvt_pk_bf16_f32 v224, v94, v95
	v_cvt_pk_bf16_f32 v225, v96, v97
	v_cvt_pk_bf16_f32 v226, v86, v87
	v_cvt_pk_bf16_f32 v227, v88, v89
	v_cvt_pk_bf16_f32 v228, v82, v83
	v_cvt_pk_bf16_f32 v229, v84, v85
	v_permlane16_swap_b32_e32 v222, v224
	v_permlane16_swap_b32_e32 v223, v225
	v_permlane16_swap_b32_e32 v226, v228
	v_permlane16_swap_b32_e32 v227, v229
	global_store_dwordx4 v[104:105], v[222:225], off
	global_store_dwordx4 v[104:105], v[226:229], off offset:64
	s_nop 1

; template <int AI>
; __device__ __forceinline__ void epi_inproj(const Params& p, const acc8_t& acc, int g, int tbase, int fr, int fq) {
;     ...
;     if (bdst) {
;       u16* d = bdst + (brow0 + tl) * (size_t)bld + bcol;
; #pragma unroll
;       for (int bj = 0; bj < 2; bj++)
; #pragma unroll
;         for (int n = 0; n < 2; n++) {
;           uint2 o;
;           o.x = pack2(x[(bj * 2 + n) * 4 + 0], x[(bj * 2 + n) * 4 + 1]);
;           o.y = pack2(x[(bj * 2 + n) * 4 + 2], x[(bj * 2 + n) * 4 + 3]);
;           *(uint2*)(d + 32 * bj + 16 * n + 4 * fq) = o;
;         }
;     }
.LBB0_337:
	v_lshl_add_u64 v[88:89], s[38:39], 0, v[86:87]
	v_mul_lo_u32 v90, v89, s66
	v_mul_lo_u32 v91, v88, s67
	v_mad_u64_u32 v[88:89], s[10:11], v88, s66, 0
	v_add3_u32 v89, v89, v91, v90
	v_lshl_add_u64 v[88:89], v[88:89], 1, v[166:167]
	v_cvt_pk_bf16_f32 v230, v82, v83
	v_cvt_pk_bf16_f32 v231, v84, v85
	v_cvt_pk_bf16_f32 v232, v78, v79
	v_cvt_pk_bf16_f32 v233, v80, v81
	v_cvt_pk_bf16_f32 v234, v70, v71
	v_cvt_pk_bf16_f32 v235, v72, v73
	v_cvt_pk_bf16_f32 v236, v66, v67
	v_cvt_pk_bf16_f32 v237, v68, v69
	v_permlane16_swap_b32_e32 v230, v232
	v_permlane16_swap_b32_e32 v231, v233
	v_permlane16_swap_b32_e32 v234, v236
	v_permlane16_swap_b32_e32 v235, v237
	global_store_dwordx4 v[88:89], v[230:233], off
	global_store_dwordx4 v[88:89], v[234:237], off offset:64
	s_nop 1

; template <int AI>
; __device__ __forceinline__ void epi_inproj(const Params& p, const acc8_t& acc, int g, int tbase, int fr, int fq) {
;     ...
;   const bool sample = tbase >= NPROMPT;
;   int b, trow;
;   if (!sample) { b = tbase >> 13; trow = tbase & 8191; } else { b = (tbase - NPROMPT) >> 6; trow = 0; }
;   const float* gain = nullptr; bool rope = false, sig = false;
;   u16* bdst = nullptr; size_t brow0 = 0; int bld = 0, bcol = 0;
;   u16* vdst = nullptr; int vS = 0, vcol0 = 0;
;   float* fdst = nullptr; size_t frow0 = 0; int fld = 0, fcol = 0;
;   bool wi = false;
;   if (g < 8) { gain = p.in[9]; rope = true; bdst = (u16*)(ws + OFF_QA); brow0 = tbase; bld = 512; bcol = g * 64; }
;   else if (g < 16) {
;     int hd = g - 8; gain = p.in[10]; rope = true; bld = 64;
;     if (!sample) { bdst = (u16*)(ws + OFF_KAP) + (size_t)(b * 8 + hd) * 8192 * 64; brow0 = trow; fdst = p.out + O_KAP; frow0 = tbase; }
;     else { bdst = (u16*)(ws + OFF_KAS) + (size_t)(b * 8 + hd) * 1088 * 64; brow0 = 1024; fdst = p.out + O_KAS; frow0 = b * 64; }
;     fld = 512; fcol = hd * 64;
;   } else if (g < 24) {
;     int hd = g - 16;
;     if (!sample) { vdst = (u16*)(ws + OFF_VAP) + (size_t)(b * 8 + hd) * 64 * 8192; vS = 8192; vcol0 = trow; fdst = p.out + O_VAP; frow0 = tbase; }
;     else { vdst = (u16*)(ws + OFF_VAS) + (size_t)(b * 8 + hd) * 64 * 1088; vS = 1088; vcol0 = 1024; fdst = p.out + O_VAS; frow0 = b * 64; }
;     fld = 512; fcol = hd * 64;
;   } else if (g < 32) { rope = true; bdst = (u16*)(ws + OFF_QI); brow0 = tbase; bld = 512; bcol = (g - 24) * 64; }
;   else if (g == 32) {
;     gain = p.in[11]; rope = true; bld = 64; fld = 64;
;     if (!sample) { bdst = (u16*)(ws + OFF_KIP) + (size_t)b * 8192 * 64; brow0 = trow; fdst = p.out + O_KIP; frow0 = tbase; }
;     else { bdst = (u16*)(ws + OFF_KIS) + (size_t)b * 1088 * 64; brow0 = 1024; fdst = p.out + O_KIS; frow0 = b * 64; }
;   } else if (g < 41) { gain = p.in[12]; bdst = (u16*)(ws + OFF_QB); brow0 = tbase; bld = 512; bcol = (g - 33) * 64; }
;   else if (g < 49) {
;     int hd = g - 41; gain = p.in[13]; bld = 64; fld = 512; fcol = hd * 64;
;     if (!sample) {
;       bdst = (u16*)(ws + OFF_KBP) + (size_t)(b * 8 + hd) * 8192 * 64; brow0 = trow;
;       if (trow >= 7680) { fdst = p.out + O_KBP; frow0 = b * 512 + (trow - 7680); }
.LBB0_394:
	s_xor_b64 s[22:23], s[22:23], -1
	s_and_b64 s[4:5], s[4:5], exec
	s_cselect_b32 s0, 0x400, s64
	s_cmp_lg_u64 s[12:13], 0
	s_cselect_b64 s[94:95], -1, 0
	s_ashr_i32 s85, s84, 31
	s_lshl_b64 s[6:7], s[84:85], 1
	s_add_u32 s6, s12, s6
	s_addc_u32 s7, s13, s7
	s_cmp_lg_u64 s[18:19], 0
	v_and_b32_e32 v84, 4, v82
	s_cselect_b64 s[92:93], -1, 0
	s_lshr_b32 s64, s1, 6
	v_lshlrev_b32_e32 v154, 3, v84
	v_and_b32_e32 v84, 1, v160
	s_lshl_b64 s[12:13], s[64:65], 13
	v_cmp_eq_u32_e64 s[8:9], 0, v84
	v_and_b32_e32 v84, 2, v160
	s_add_u32 s12, s18, s12
	v_lshl_add_u64 v[90:91], v[82:83], 1, s[6:7]
	v_and_b32_e32 v206, 1, v192
	v_mov_b32_e32 v207, 0
	v_mul_u32_u24_e32 v206, 24, v206
	v_lshl_add_u64 v[90:91], v[90:91], 0, v[206:207]
	v_cmp_eq_u32_e64 s[6:7], 0, v84
	s_addc_u32 s13, s19, s13
	v_and_b32_e32 v84, -4, v160
	v_ashrrev_i32_e32 v85, 31, v84
	s_cmp_lg_u64 s[28:29], 0
	s_mov_b32 s43, s65
	v_lshl_add_u64 v[88:89], v[84:85], 1, s[12:13]
	s_cselect_b64 s[84:85], -1, 0
	s_lshl_b64 s[12:13], s[42:43], 2
	s_add_u32 s12, s28, s12
	s_addc_u32 s13, s29, s13
	v_lshlrev_b64 v[94:95], 2, v[82:83]
	v_cndmask_b32_e64 v82, 0, 1, s[10:11]
	v_readlane_b32 s28, v238, 26
	v_lshl_add_u64 v[92:93], s[52:53], 0, v[154:155]
	v_cmp_gt_i32_e64 s[4:5], 2, v192
	v_lshl_add_u64 v[86:87], s[12:13], 0, v[94:95]
	s_mov_b64 s[12:13], -1
	s_and_b64 vcc, s[82:83], s[22:23]
	s_andn2_b64 vcc, exec, vcc
	s_cbranch_vccnz .Lp1cs_b_skip
	v_add_u32_e32 v210, s0, v160
	v_ashrrev_i32_e32 v211, 31, v210
	v_lshlrev_b64 v[210:211], 6, v[210:211]
	v_lshl_add_u64 v[210:211], v[92:93], 0, v[210:211]
	global_load_dwordx4 v[206:209], v[210:211], off offset:16
	s_nop 0
	global_load_dwordx4 v[210:213], v[210:211], off
	v_add3_u32 v218, s0, v160, 16
	v_ashrrev_i32_e32 v219, 31, v218
	v_lshlrev_b64 v[218:219], 6, v[218:219]
	v_lshl_add_u64 v[218:219], v[92:93], 0, v[218:219]
	global_load_dwordx4 v[214:217], v[218:219], off offset:16
	s_nop 0
	global_load_dwordx4 v[218:221], v[218:219], off
	v_add3_u32 v226, s0, v160, 32
	v_ashrrev_i32_e32 v227, 31, v226
	v_lshlrev_b64 v[226:227], 6, v[226:227]
	v_lshl_add_u64 v[226:227], v[92:93], 0, v[226:227]
	global_load_dwordx4 v[222:225], v[226:227], off offset:16
	s_nop 0
	global_load_dwordx4 v[226:229], v[226:227], off
	v_add3_u32 v234, s0, v160, 48
	v_ashrrev_i32_e32 v235, 31, v234
	v_lshlrev_b64 v[234:235], 6, v[234:235]
	v_lshl_add_u64 v[234:235], v[92:93], 0, v[234:235]
	global_load_dwordx4 v[230:233], v[234:235], off offset:16
	s_nop 0
	global_load_dwordx4 v[234:237], v[234:235], off

; template <int AI>
; __device__ __forceinline__ void epi_inproj(const Params& p, const acc8_t& acc, int g, int tbase, int fr, int fq) {
;     ...
;     if (bdst) {
;       u16* d = bdst + (brow0 + tl) * (size_t)bld + bcol;
; #pragma unroll
;       for (int bj = 0; bj < 2; bj++)
; #pragma unroll
;         for (int n = 0; n < 2; n++) {
;           uint2 o;
;           o.x = pack2(x[(bj * 2 + n) * 4 + 0], x[(bj * 2 + n) * 4 + 1]);
;           o.y = pack2(x[(bj * 2 + n) * 4 + 2], x[(bj * 2 + n) * 4 + 3]);
;           *(uint2*)(d + 32 * bj + 16 * n + 4 * fq) = o;
;         }
;     }
.LBB0_400:
	v_lshl_add_u64 v[96:97], s[38:39], 0, v[160:161]
	v_mul_lo_u32 v98, v97, s24
	v_mul_lo_u32 v99, v96, s25
	v_mad_u64_u32 v[96:97], s[12:13], v96, s24, 0
	v_add3_u32 v97, v97, v99, v98
	v_lshl_add_u64 v[96:97], v[96:97], 1, v[90:91]
	v_cvt_pk_bf16_f32 v206, v82, v83
	v_cvt_pk_bf16_f32 v207, v84, v85
	v_cvt_pk_bf16_f32 v208, v62, v63
	v_cvt_pk_bf16_f32 v209, v64, v65
	v_cvt_pk_bf16_f32 v210, v54, v55
	v_cvt_pk_bf16_f32 v211, v56, v57
	v_cvt_pk_bf16_f32 v212, v50, v51
	v_cvt_pk_bf16_f32 v213, v52, v53
	v_permlane16_swap_b32_e32 v206, v208
	v_permlane16_swap_b32_e32 v207, v209
	v_permlane16_swap_b32_e32 v210, v212
	v_permlane16_swap_b32_e32 v211, v213
	global_store_dwordx4 v[96:97], v[206:209], off
	global_store_dwordx4 v[96:97], v[210:213], off offset:64
	s_nop 1

; template <int AI>
; __device__ __forceinline__ void epi_inproj(const Params& p, const acc8_t& acc, int g, int tbase, int fr, int fq) {
;     ...
;     if (bdst) {
;       u16* d = bdst + (brow0 + tl) * (size_t)bld + bcol;
; #pragma unroll
;       for (int bj = 0; bj < 2; bj++)
; #pragma unroll
;         for (int n = 0; n < 2; n++) {
;           uint2 o;
;           o.x = pack2(x[(bj * 2 + n) * 4 + 0], x[(bj * 2 + n) * 4 + 1]);
;           o.y = pack2(x[(bj * 2 + n) * 4 + 2], x[(bj * 2 + n) * 4 + 3]);
;           *(uint2*)(d + 32 * bj + 16 * n + 4 * fq) = o;
;         }
;     }
.LBB0_420:
	v_lshl_add_u64 v[58:59], s[38:39], 0, v[56:57]
	v_mul_lo_u32 v60, v59, s24
	v_mul_lo_u32 v61, v58, s25
	v_mad_u64_u32 v[58:59], s[18:19], v58, s24, 0
	v_add3_u32 v59, v59, v61, v60
	v_lshl_add_u64 v[58:59], v[58:59], 1, v[90:91]
	v_cvt_pk_bf16_f32 v214, v50, v51
	v_cvt_pk_bf16_f32 v215, v52, v53
	v_cvt_pk_bf16_f32 v216, v46, v47
	v_cvt_pk_bf16_f32 v217, v48, v49
	v_cvt_pk_bf16_f32 v218, v38, v39
	v_cvt_pk_bf16_f32 v219, v40, v41
	v_cvt_pk_bf16_f32 v220, v34, v35
	v_cvt_pk_bf16_f32 v221, v36, v37
	v_permlane16_swap_b32_e32 v214, v216
	v_permlane16_swap_b32_e32 v215, v217
	v_permlane16_swap_b32_e32 v218, v220
	v_permlane16_swap_b32_e32 v219, v221
	global_store_dwordx4 v[58:59], v[214:217], off
	global_store_dwordx4 v[58:59], v[218:221], off offset:64
	s_nop 1

; template <int AI>
; __device__ __forceinline__ void epi_inproj(const Params& p, const acc8_t& acc, int g, int tbase, int fr, int fq) {
;     ...
;     if (bdst) {
;       u16* d = bdst + (brow0 + tl) * (size_t)bld + bcol;
; #pragma unroll
;       for (int bj = 0; bj < 2; bj++)
; #pragma unroll
;         for (int n = 0; n < 2; n++) {
;           uint2 o;
;           o.x = pack2(x[(bj * 2 + n) * 4 + 0], x[(bj * 2 + n) * 4 + 1]);
;           o.y = pack2(x[(bj * 2 + n) * 4 + 2], x[(bj * 2 + n) * 4 + 3]);
;           *(uint2*)(d + 32 * bj + 16 * n + 4 * fq) = o;
;         }
;     }
.LBB0_434:
	v_lshl_add_u64 v[40:41], s[38:39], 0, v[38:39]
	v_mul_lo_u32 v42, v41, s24
	v_mul_lo_u32 v43, v40, s25
	v_mad_u64_u32 v[40:41], s[18:19], v40, s24, 0
	v_add3_u32 v41, v41, v43, v42
	v_lshl_add_u64 v[40:41], v[40:41], 1, v[90:91]
	v_cvt_pk_bf16_f32 v222, v34, v35
	v_cvt_pk_bf16_f32 v223, v36, v37
	v_cvt_pk_bf16_f32 v224, v30, v31
	v_cvt_pk_bf16_f32 v225, v32, v33
	v_cvt_pk_bf16_f32 v226, v22, v23
	v_cvt_pk_bf16_f32 v227, v24, v25
	v_cvt_pk_bf16_f32 v228, v18, v19
	v_cvt_pk_bf16_f32 v229, v20, v21
	v_permlane16_swap_b32_e32 v222, v224
	v_permlane16_swap_b32_e32 v223, v225
	v_permlane16_swap_b32_e32 v226, v228
	v_permlane16_swap_b32_e32 v227, v229
	global_store_dwordx4 v[40:41], v[222:225], off
	global_store_dwordx4 v[40:41], v[226:229], off offset:64
	s_nop 1

; template <int AI>
; __device__ __forceinline__ void epi_inproj(const Params& p, const acc8_t& acc, int g, int tbase, int fr, int fq) {
;     ...
;     if (bdst) {
;       u16* d = bdst + (brow0 + tl) * (size_t)bld + bcol;
; #pragma unroll
;       for (int bj = 0; bj < 2; bj++)
; #pragma unroll
;         for (int n = 0; n < 2; n++) {
;           uint2 o;
;           o.x = pack2(x[(bj * 2 + n) * 4 + 0], x[(bj * 2 + n) * 4 + 1]);
;           o.y = pack2(x[(bj * 2 + n) * 4 + 2], x[(bj * 2 + n) * 4 + 3]);
;           *(uint2*)(d + 32 * bj + 16 * n + 4 * fq) = o;
;         }
;     }
.LBB0_448:
	v_lshl_add_u64 v[24:25], s[38:39], 0, v[22:23]
	v_mul_lo_u32 v26, v25, s24
	v_mul_lo_u32 v27, v24, s25
	v_mad_u64_u32 v[24:25], s[0:1], v24, s24, 0
	v_add3_u32 v25, v25, v27, v26
	v_lshl_add_u64 v[24:25], v[24:25], 1, v[90:91]
	v_cvt_pk_bf16_f32 v230, v18, v19
	v_cvt_pk_bf16_f32 v231, v20, v21
	v_cvt_pk_bf16_f32 v232, v14, v15
	v_cvt_pk_bf16_f32 v233, v16, v17
	v_cvt_pk_bf16_f32 v234, v10, v11
	v_cvt_pk_bf16_f32 v235, v12, v13
	v_cvt_pk_bf16_f32 v236, v2, v3
	v_cvt_pk_bf16_f32 v237, v4, v5
	v_permlane16_swap_b32_e32 v230, v232
	v_permlane16_swap_b32_e32 v231, v233
	v_permlane16_swap_b32_e32 v234, v236
	v_permlane16_swap_b32_e32 v235, v237
	global_store_dwordx4 v[24:25], v[230:233], off
	global_store_dwordx4 v[24:25], v[234:237], off offset:64
	s_nop 1

; #define PG8_STAGE(bufoff, gbase, voff) do { _Pragma("unroll") for (int _i = 0; _i < 2; ++_i) \
;         __builtin_amdgcn_global_load_lds((const unsigned*)((const char*)(gbase) + (voff)[_i]), (PG8_LAS unsigned*)(lds + (bufoff) + ldsw + _i * 8192), 16, 0, 0); } while (0)
; #define PG8_LDA(dst, b, h) do { _Pragma("unroll") for (int m = 0; m < 4; ++m) _Pragma("unroll") for (int k = 0; k < 2; ++k) dst[m][k] = *(const PG8_LAS bf16x8*)(lds + PG8_SA(b, h) + aoff + m * 2048 + k * 1024); } while (0)
; #define PG8_LDB(dst, b, h) do { _Pragma("unroll") for (int n = 0; n < 2; ++n) _Pragma("unroll") for (int k = 0; k < 2; ++k) dst[n][k] = *(const PG8_LAS bf16x8*)(lds + PG8_SB(b, h) + boff + n * 2048 + k * 1024); } while (0)
; #define PG8_MMA(ai, bj, At, Bt) do { __builtin_amdgcn_s_setprio(1); _Pragma("unroll") for (int m = 0; m < 4; ++m) _Pragma("unroll") for (int n = 0; n < 2; ++n) _Pragma("unroll") for (int k = 0; k < 2; ++k) \
;         acc[ai][bj][m][n] = __builtin_amdgcn_mfma_f32_16x16x32_bf16(Bt[n][k], At[m][k], acc[ai][bj][m][n], 0, 0, 0); __builtin_amdgcn_s_setprio(0); } while (0)
; #define PG8_WAIT_V(n) asm volatile("s_waitcnt vmcnt(" #n ")" ::: "memory")
; #define PG8_WAIT_L(n) asm volatile("s_waitcnt lgkmcnt(" #n ")" ::: "memory")
; #define PG8_BAR __builtin_amdgcn_s_barrier()
; #define PG8_SCHED __builtin_amdgcn_sched_barrier(0)
; template <class Epi, class Sched>
; __device__ __forceinline__ void gemm_phase(PG8_LAS unsigned char* lds, const Gemm g, const Sched& S, const Epi& E) {
;     ...
;             PG8_LDB(B0, 0, 0); PG8_SCHED; PG8_LDA(At, 0, 0); PG8_STAGE(PG8_SA(1, 1), a1 + hstep, voffA);
;             PG8_WAIT_L(8); PG8_BAR; PG8_WAIT_L(0); PG8_MMA(0, 0, At, B0); PG8_BAR; PG8_SCHED;
;             PG8_LDB(B1, 0, 1); PG8_STAGE(PG8_SB(0, 0), b2, voffB);
;             PG8_BAR; PG8_WAIT_L(0); PG8_MMA(0, 1, At, B1); PG8_BAR;
;             PG8_LDA(At, 0, 1); PG8_STAGE(PG8_SA(0, 0), a2, voffA);
;             PG8_BAR; PG8_WAIT_L(0); PG8_MMA(1, 0, At, B0); PG8_BAR; PG8_SCHED;
;             PG8_STAGE(PG8_SB(0, 1), b2 + hstep, voffB);
;             PG8_WAIT_V(6); PG8_BAR; PG8_MMA(1, 1, At, B1); PG8_BAR;
.LBB0_750:
	ds_read_b128 v[138:141], v147
	ds_read_b128 v[164:167], v148
	ds_read_b128 v[168:171], v149
	ds_read_b128 v[172:175], v150
	s_add_u32 s30, s28, 0xfffc0080
	s_addc_u32 s31, s29, -1
	s_cmp_eq_u32 s64, 12
	s_cselect_b32 s35, s17, s31
	s_cselect_b32 s34, s25, s30
	s_cselect_b32 s31, s15, s63
	s_cselect_b32 s30, s61, s62
	s_mov_b32 m0, s59
	v_lshl_add_u64 v[142:143], s[28:29], 0, v[134:135]
	ds_read_b128 v[176:179], v145
	ds_read_b128 v[180:183], v145 offset:1024
	ds_read_b128 v[184:187], v145 offset:2048
	ds_read_b128 v[188:191], v145 offset:3072
	ds_read_b128 v[192:195], v145 offset:4096
	ds_read_b128 v[196:199], v145 offset:5120
	ds_read_b128 v[200:203], v145 offset:6144
	ds_read_b128 v[204:207], v145 offset:7168
	global_load_lds_dwordx4 v[142:143], off
	v_lshl_add_u64 v[142:143], s[28:29], 0, v[136:137]
	s_mov_b32 m0, s60
	s_nop 0
	global_load_lds_dwordx4 v[142:143], off
	s_waitcnt lgkmcnt(8)
	s_barrier
	s_waitcnt lgkmcnt(0)
	s_setprio 1
	s_waitcnt lgkmcnt(0)
	v_mfma_f32_16x16x32_bf16 v[126:129], v[138:141], v[176:179], v[126:129]
	v_mfma_f32_16x16x32_bf16 v[122:125], v[168:171], v[176:179], v[122:125]
	v_mfma_f32_16x16x32_bf16 v[110:113], v[138:141], v[184:187], v[110:113]
	v_mfma_f32_16x16x32_bf16 v[106:109], v[168:171], v[184:187], v[106:109]
	v_mfma_f32_16x16x32_bf16 v[94:97], v[138:141], v[192:195], v[94:97]
	v_mfma_f32_16x16x32_bf16 v[90:93], v[168:171], v[192:195], v[90:93]
	v_mfma_f32_16x16x32_bf16 v[78:81], v[138:141], v[200:203], v[78:81]
	v_mfma_f32_16x16x32_bf16 v[74:77], v[168:171], v[200:203], v[74:77]
	v_mfma_f32_16x16x32_bf16 v[126:129], v[164:167], v[180:183], v[126:129]
	v_mfma_f32_16x16x32_bf16 v[122:125], v[172:175], v[180:183], v[122:125]
	v_mfma_f32_16x16x32_bf16 v[110:113], v[164:167], v[188:191], v[110:113]
	v_mfma_f32_16x16x32_bf16 v[106:109], v[172:175], v[188:191], v[106:109]
	v_mfma_f32_16x16x32_bf16 v[94:97], v[164:167], v[196:199], v[94:97]
	v_mfma_f32_16x16x32_bf16 v[90:93], v[172:175], v[196:199], v[90:93]
	v_mfma_f32_16x16x32_bf16 v[78:81], v[164:167], v[204:207], v[78:81]
	v_mfma_f32_16x16x32_bf16 v[74:77], v[172:175], v[204:207], v[74:77]
	s_setprio 0
	s_barrier
	s_mov_b32 m0, s27
	v_lshl_add_u64 v[142:143], s[30:31], 0, v[130:131]
	ds_read_b128 v[208:211], v151
	ds_read_b128 v[212:215], v152
	ds_read_b128 v[216:219], v153
	ds_read_b128 v[220:223], v154
	global_load_lds_dwordx4 v[142:143], off
	v_lshl_add_u64 v[224:225], s[30:31], 0, v[132:133]
	s_mov_b32 m0, s41
	s_nop 0
	global_load_lds_dwordx4 v[224:225], off
	s_barrier
	s_waitcnt lgkmcnt(0)
	s_setprio 1
	s_waitcnt lgkmcnt(0)
	v_mfma_f32_16x16x32_bf16 v[118:121], v[208:211], v[176:179], v[118:121]
	v_mfma_f32_16x16x32_bf16 v[114:117], v[216:219], v[176:179], v[114:117]
	v_mfma_f32_16x16x32_bf16 v[102:105], v[208:211], v[184:187], v[102:105]
	v_mfma_f32_16x16x32_bf16 v[98:101], v[216:219], v[184:187], v[98:101]
	v_mfma_f32_16x16x32_bf16 v[86:89], v[208:211], v[192:195], v[86:89]
	v_mfma_f32_16x16x32_bf16 v[82:85], v[216:219], v[192:195], v[82:85]
	v_mfma_f32_16x16x32_bf16 v[70:73], v[208:211], v[200:203], v[70:73]
	v_mfma_f32_16x16x32_bf16 v[66:69], v[216:219], v[200:203], v[66:69]
	v_mfma_f32_16x16x32_bf16 v[118:121], v[212:215], v[180:183], v[118:121]
	v_mfma_f32_16x16x32_bf16 v[114:117], v[220:223], v[180:183], v[114:117]
	v_mfma_f32_16x16x32_bf16 v[102:105], v[212:215], v[188:191], v[102:105]
	v_mfma_f32_16x16x32_bf16 v[98:101], v[220:223], v[188:191], v[98:101]
	v_mfma_f32_16x16x32_bf16 v[86:89], v[212:215], v[196:199], v[86:89]
	v_mfma_f32_16x16x32_bf16 v[82:85], v[220:223], v[196:199], v[82:85]
	v_mfma_f32_16x16x32_bf16 v[70:73], v[212:215], v[204:207], v[70:73]
	v_mfma_f32_16x16x32_bf16 v[66:69], v[220:223], v[204:207], v[66:69]
	s_setprio 0
	s_mov_b32 m0, s40
	v_lshl_add_u64 v[226:227], s[34:35], 0, v[130:131]
	s_barrier
	ds_read_b128 v[176:179], v145 offset:16384
	ds_read_b128 v[180:183], v145 offset:17408
	ds_read_b128 v[184:187], v145 offset:18432
	ds_read_b128 v[188:191], v145 offset:19456
	ds_read_b128 v[192:195], v145 offset:20480
	ds_read_b128 v[196:199], v145 offset:21504
	ds_read_b128 v[200:203], v145 offset:22528
	ds_read_b128 v[204:207], v145 offset:23552
	global_load_lds_dwordx4 v[226:227], off
	v_lshl_add_u64 v[228:229], s[34:35], 0, v[132:133]
	s_mov_b32 m0, s42
	s_nop 0
	global_load_lds_dwordx4 v[228:229], off
	s_barrier
	s_waitcnt lgkmcnt(0)
	s_setprio 1
	s_waitcnt lgkmcnt(0)
	v_mfma_f32_16x16x32_bf16 v[62:65], v[138:141], v[176:179], v[62:65]
	v_mfma_f32_16x16x32_bf16 v[58:61], v[168:171], v[176:179], v[58:61]
	v_mfma_f32_16x16x32_bf16 v[46:49], v[138:141], v[184:187], v[46:49]
	v_mfma_f32_16x16x32_bf16 v[42:45], v[168:171], v[184:187], v[42:45]
	v_mfma_f32_16x16x32_bf16 v[30:33], v[138:141], v[192:195], v[30:33]
	v_mfma_f32_16x16x32_bf16 v[26:29], v[168:171], v[192:195], v[26:29]
	v_mfma_f32_16x16x32_bf16 v[14:17], v[138:141], v[200:203], v[14:17]
	v_mfma_f32_16x16x32_bf16 v[10:13], v[168:171], v[200:203], v[10:13]
	v_mfma_f32_16x16x32_bf16 v[62:65], v[164:167], v[180:183], v[62:65]
	v_mfma_f32_16x16x32_bf16 v[58:61], v[172:175], v[180:183], v[58:61]
	v_mfma_f32_16x16x32_bf16 v[46:49], v[164:167], v[188:191], v[46:49]
	v_mfma_f32_16x16x32_bf16 v[42:45], v[172:175], v[188:191], v[42:45]
	v_mfma_f32_16x16x32_bf16 v[30:33], v[164:167], v[196:199], v[30:33]
	v_mfma_f32_16x16x32_bf16 v[26:29], v[172:175], v[196:199], v[26:29]
	v_mfma_f32_16x16x32_bf16 v[14:17], v[164:167], v[204:207], v[14:17]
	v_mfma_f32_16x16x32_bf16 v[10:13], v[172:175], v[204:207], v[10:13]
	s_setprio 0
	s_barrier
; #define PG8_STAGE(bufoff, gbase, voff) do { _Pragma("unroll") for (int _i = 0; _i < 2; ++_i) \
;         __builtin_amdgcn_global_load_lds((const unsigned*)((const char*)(gbase) + (voff)[_i]), (PG8_LAS unsigned*)(lds + (bufoff) + ldsw + _i * 8192), 16, 0, 0); } while (0)
; #define PG8_LDA(dst, b, h) do { _Pragma("unroll") for (int m = 0; m < 4; ++m) _Pragma("unroll") for (int k = 0; k < 2; ++k) dst[m][k] = *(const PG8_LAS bf16x8*)(lds + PG8_SA(b, h) + aoff + m * 2048 + k * 1024); } while (0)
; #define PG8_LDB(dst, b, h) do { _Pragma("unroll") for (int n = 0; n < 2; ++n) _Pragma("unroll") for (int k = 0; k < 2; ++k) dst[n][k] = *(const PG8_LAS bf16x8*)(lds + PG8_SB(b, h) + boff + n * 2048 + k * 1024); } while (0)
; #define PG8_MMA(ai, bj, At, Bt) do { __builtin_amdgcn_s_setprio(1); _Pragma("unroll") for (int m = 0; m < 4; ++m) _Pragma("unroll") for (int n = 0; n < 2; ++n) _Pragma("unroll") for (int k = 0; k < 2; ++k) \
;         acc[ai][bj][m][n] = __builtin_amdgcn_mfma_f32_16x16x32_bf16(Bt[n][k], At[m][k], acc[ai][bj][m][n], 0, 0, 0); __builtin_amdgcn_s_setprio(0); } while (0)
; #define PG8_WAIT_L(n) asm volatile("s_waitcnt lgkmcnt(" #n ")" ::: "memory")
; #define PG8_BAR __builtin_amdgcn_s_barrier()
; #define PG8_SCHED __builtin_amdgcn_sched_barrier(0)
; template <class Epi, class Sched>
; __device__ __forceinline__ void gemm_phase(PG8_LAS unsigned char* lds, const Gemm g, const Sched& S, const Epi& E) {
;     ...
;             PG8_LDB(B0, 1, 0); PG8_SCHED; PG8_LDA(At, 1, 0); PG8_STAGE(PG8_SA(0, 1), a2 + hstep, voffA);
;             PG8_WAIT_L(8); PG8_BAR; PG8_WAIT_L(0); PG8_MMA(0, 0, At, B0); PG8_BAR; PG8_SCHED;
;             PG8_LDB(B1, 1, 1); PG8_STAGE(PG8_SB(1, 0), b3, voffB);
;             PG8_BAR; PG8_WAIT_L(0); PG8_MMA(0, 1, At, B1); PG8_BAR;
;             PG8_LDA(At, 1, 1); PG8_STAGE(PG8_SA(1, 0), a3, voffA);
;             PG8_BAR; PG8_WAIT_L(0); PG8_MMA(1, 0, At, B0); PG8_BAR; PG8_SCHED;
	s_add_u32 s66, s30, 0x40000
	s_addc_u32 s67, s31, 0
	s_mov_b32 m0, s43
	v_lshl_add_u64 v[138:139], s[66:67], 0, v[130:131]
	global_load_lds_dwordx4 v[138:139], off
	v_lshl_add_u64 v[138:139], s[66:67], 0, v[132:133]
	s_mov_b32 m0, s44
	s_nop 0
	global_load_lds_dwordx4 v[138:139], off
	s_waitcnt vmcnt(6)
	s_barrier
	s_setprio 1
	v_mfma_f32_16x16x32_bf16 v[54:57], v[208:211], v[176:179], v[54:57]
	v_mfma_f32_16x16x32_bf16 v[50:53], v[216:219], v[176:179], v[50:53]
	v_mfma_f32_16x16x32_bf16 v[38:41], v[208:211], v[184:187], v[38:41]
	v_mfma_f32_16x16x32_bf16 v[34:37], v[216:219], v[184:187], v[34:37]
	v_mfma_f32_16x16x32_bf16 v[22:25], v[208:211], v[192:195], v[22:25]
	v_mfma_f32_16x16x32_bf16 v[18:21], v[216:219], v[192:195], v[18:21]
	v_mfma_f32_16x16x32_bf16 v[6:9], v[208:211], v[200:203], v[6:9]
	v_mfma_f32_16x16x32_bf16 v[2:5], v[216:219], v[200:203], v[2:5]
	v_mfma_f32_16x16x32_bf16 v[54:57], v[212:215], v[180:183], v[54:57]
	v_mfma_f32_16x16x32_bf16 v[50:53], v[220:223], v[180:183], v[50:53]
	v_mfma_f32_16x16x32_bf16 v[38:41], v[212:215], v[188:191], v[38:41]
	v_mfma_f32_16x16x32_bf16 v[34:37], v[220:223], v[188:191], v[34:37]
	v_mfma_f32_16x16x32_bf16 v[22:25], v[212:215], v[196:199], v[22:25]
	v_mfma_f32_16x16x32_bf16 v[18:21], v[220:223], v[196:199], v[18:21]
	v_mfma_f32_16x16x32_bf16 v[6:9], v[212:215], v[204:207], v[6:9]
	v_mfma_f32_16x16x32_bf16 v[2:5], v[220:223], v[204:207], v[2:5]
	s_setprio 0
	s_barrier
	ds_read_b128 v[138:141], v155
	ds_read_b128 v[164:167], v156
	ds_read_b128 v[168:171], v157
	ds_read_b128 v[172:175], v158
	s_add_u32 s34, s34, 0x40000
	s_addc_u32 s35, s35, 0
	s_mov_b32 m0, s45
	v_lshl_add_u64 v[208:209], s[34:35], 0, v[130:131]
	ds_read_b128 v[176:179], v145 offset:32768
	ds_read_b128 v[180:183], v145 offset:33792
	ds_read_b128 v[184:187], v145 offset:34816
	ds_read_b128 v[188:191], v145 offset:35840
	ds_read_b128 v[192:195], v145 offset:36864
	ds_read_b128 v[196:199], v145 offset:37888
	ds_read_b128 v[200:203], v145 offset:38912
	ds_read_b128 v[204:207], v145 offset:39936
	global_load_lds_dwordx4 v[208:209], off
	v_lshl_add_u64 v[208:209], s[34:35], 0, v[132:133]
	s_mov_b32 m0, s46
	s_nop 0
	global_load_lds_dwordx4 v[208:209], off
	s_waitcnt lgkmcnt(8)
	s_barrier
	s_waitcnt lgkmcnt(0)
	s_setprio 1
	s_waitcnt lgkmcnt(0)
	v_mfma_f32_16x16x32_bf16 v[126:129], v[138:141], v[176:179], v[126:129]
	v_mfma_f32_16x16x32_bf16 v[122:125], v[168:171], v[176:179], v[122:125]
	v_mfma_f32_16x16x32_bf16 v[110:113], v[138:141], v[184:187], v[110:113]
	v_mfma_f32_16x16x32_bf16 v[106:109], v[168:171], v[184:187], v[106:109]
	v_mfma_f32_16x16x32_bf16 v[94:97], v[138:141], v[192:195], v[94:97]
	v_mfma_f32_16x16x32_bf16 v[90:93], v[168:171], v[192:195], v[90:93]
	v_mfma_f32_16x16x32_bf16 v[78:81], v[138:141], v[200:203], v[78:81]
	v_mfma_f32_16x16x32_bf16 v[74:77], v[168:171], v[200:203], v[74:77]
	v_mfma_f32_16x16x32_bf16 v[126:129], v[164:167], v[180:183], v[126:129]
	v_mfma_f32_16x16x32_bf16 v[122:125], v[172:175], v[180:183], v[122:125]
	v_mfma_f32_16x16x32_bf16 v[110:113], v[164:167], v[188:191], v[110:113]
	v_mfma_f32_16x16x32_bf16 v[106:109], v[172:175], v[188:191], v[106:109]
	v_mfma_f32_16x16x32_bf16 v[94:97], v[164:167], v[196:199], v[94:97]
	v_mfma_f32_16x16x32_bf16 v[90:93], v[172:175], v[196:199], v[90:93]
	v_mfma_f32_16x16x32_bf16 v[78:81], v[164:167], v[204:207], v[78:81]
	v_mfma_f32_16x16x32_bf16 v[74:77], v[172:175], v[204:207], v[74:77]
	s_setprio 0
	s_barrier
	s_mov_b32 m0, s47
	v_lshl_add_u64 v[142:143], v[142:143], 0, s[8:9]
	ds_read_b128 v[208:211], v159
	ds_read_b128 v[212:215], v160
	ds_read_b128 v[216:219], v161
	ds_read_b128 v[220:223], v162
	global_load_lds_dwordx4 v[142:143], off
	v_lshl_add_u64 v[142:143], v[224:225], 0, s[8:9]
	s_mov_b32 m0, s48
	s_nop 0
	global_load_lds_dwordx4 v[142:143], off
	s_barrier
	s_waitcnt lgkmcnt(0)
	s_setprio 1
	s_waitcnt lgkmcnt(0)
	v_mfma_f32_16x16x32_bf16 v[118:121], v[208:211], v[176:179], v[118:121]
	v_mfma_f32_16x16x32_bf16 v[114:117], v[216:219], v[176:179], v[114:117]
	v_mfma_f32_16x16x32_bf16 v[102:105], v[208:211], v[184:187], v[102:105]
	v_mfma_f32_16x16x32_bf16 v[98:101], v[216:219], v[184:187], v[98:101]
	v_mfma_f32_16x16x32_bf16 v[86:89], v[208:211], v[192:195], v[86:89]
	v_mfma_f32_16x16x32_bf16 v[82:85], v[216:219], v[192:195], v[82:85]
	v_mfma_f32_16x16x32_bf16 v[70:73], v[208:211], v[200:203], v[70:73]
	v_mfma_f32_16x16x32_bf16 v[66:69], v[216:219], v[200:203], v[66:69]
	v_mfma_f32_16x16x32_bf16 v[118:121], v[212:215], v[180:183], v[118:121]
	v_mfma_f32_16x16x32_bf16 v[114:117], v[220:223], v[180:183], v[114:117]
	v_mfma_f32_16x16x32_bf16 v[102:105], v[212:215], v[188:191], v[102:105]
	v_mfma_f32_16x16x32_bf16 v[98:101], v[220:223], v[188:191], v[98:101]
	v_mfma_f32_16x16x32_bf16 v[86:89], v[212:215], v[196:199], v[86:89]
	v_mfma_f32_16x16x32_bf16 v[82:85], v[220:223], v[196:199], v[82:85]
	v_mfma_f32_16x16x32_bf16 v[70:73], v[212:215], v[204:207], v[70:73]
	v_mfma_f32_16x16x32_bf16 v[66:69], v[220:223], v[204:207], v[66:69]
	s_setprio 0
	s_mov_b32 m0, s49
	v_lshl_add_u64 v[142:143], v[226:227], 0, s[8:9]
	s_barrier
	ds_read_b128 v[176:179], v145 offset:49152
	ds_read_b128 v[180:183], v145 offset:50176
	ds_read_b128 v[184:187], v145 offset:51200
	ds_read_b128 v[188:191], v145 offset:52224
	ds_read_b128 v[192:195], v145 offset:53248
	ds_read_b128 v[196:199], v145 offset:54272
	ds_read_b128 v[200:203], v145 offset:55296
	ds_read_b128 v[204:207], v145 offset:56320
	global_load_lds_dwordx4 v[142:143], off
	v_lshl_add_u64 v[142:143], v[228:229], 0, s[8:9]
	s_mov_b32 m0, s50
	s_nop 0
	global_load_lds_dwordx4 v[142:143], off
	s_barrier
; #define PG8_STAGE(bufoff, gbase, voff) do { _Pragma("unroll") for (int _i = 0; _i < 2; ++_i) \
;         __builtin_amdgcn_global_load_lds((const unsigned*)((const char*)(gbase) + (voff)[_i]), (PG8_LAS unsigned*)(lds + (bufoff) + ldsw + _i * 8192), 16, 0, 0); } while (0)
; #define PG8_MMA(ai, bj, At, Bt) do { __builtin_amdgcn_s_setprio(1); _Pragma("unroll") for (int m = 0; m < 4; ++m) _Pragma("unroll") for (int n = 0; n < 2; ++n) _Pragma("unroll") for (int k = 0; k < 2; ++k) \
;         acc[ai][bj][m][n] = __builtin_amdgcn_mfma_f32_16x16x32_bf16(Bt[n][k], At[m][k], acc[ai][bj][m][n], 0, 0, 0); __builtin_amdgcn_s_setprio(0); } while (0)
; #define PG8_WAIT_V(n) asm volatile("s_waitcnt vmcnt(" #n ")" ::: "memory")
; #define PG8_WAIT_L(n) asm volatile("s_waitcnt lgkmcnt(" #n ")" ::: "memory")
; #define PG8_BAR __builtin_amdgcn_s_barrier()
; #define PG8_SCHED __builtin_amdgcn_sched_barrier(0)
; template <class Epi, class Sched>
; __device__ __forceinline__ void gemm_phase(PG8_LAS unsigned char* lds, const Gemm g, const Sched& S, const Epi& E) {
;     ...
;             PG8_BAR; PG8_WAIT_L(0); PG8_MMA(1, 0, At, B0); PG8_BAR; PG8_SCHED;
;             PG8_STAGE(PG8_SB(1, 1), b3 + hstep, voffB);
;             PG8_WAIT_V(6); PG8_BAR; PG8_MMA(1, 1, At, B1); PG8_BAR;
;   __device__ __forceinline__ void operator()(const acc8_t& acc, const pg8::Unit& u, int wr, int wc, int fr, int fq) const {
;     u16* X1B = (u16*)(p.ws + OFF_X1B);
;     float* rss = (float*)(p.ws + OFF_ROWSS);
; #pragma unroll
;     for (int ai = 0; ai < 2; ai++)
; #pragma unroll
;       for (int m = 0; m < 4; m++) {
;         const int token = (int)EPI_TOKEN(u, ai, m);
;         const float* xr = xrow(p, token);
;         float ss = 0.f;
; #pragma unroll
;         for (int bj = 0; bj < 2; bj++)
; #pragma unroll
;           for (int n = 0; n < 2; n++) {
;             const int f = EPI_COL(u, bj, n);
;             const float4 xv = *(const float4*)(xr + f);
	s_waitcnt lgkmcnt(0)
	s_setprio 1
	s_waitcnt lgkmcnt(0)
	v_mfma_f32_16x16x32_bf16 v[62:65], v[138:141], v[176:179], v[62:65]
	v_mfma_f32_16x16x32_bf16 v[58:61], v[168:171], v[176:179], v[58:61]
	v_mfma_f32_16x16x32_bf16 v[46:49], v[138:141], v[184:187], v[46:49]
	v_mfma_f32_16x16x32_bf16 v[42:45], v[168:171], v[184:187], v[42:45]
	v_mfma_f32_16x16x32_bf16 v[30:33], v[138:141], v[192:195], v[30:33]
	v_mfma_f32_16x16x32_bf16 v[26:29], v[168:171], v[192:195], v[26:29]
	v_mfma_f32_16x16x32_bf16 v[14:17], v[138:141], v[200:203], v[14:17]
	v_mfma_f32_16x16x32_bf16 v[10:13], v[168:171], v[200:203], v[10:13]
	v_mfma_f32_16x16x32_bf16 v[62:65], v[164:167], v[180:183], v[62:65]
	v_mfma_f32_16x16x32_bf16 v[58:61], v[172:175], v[180:183], v[58:61]
	v_mfma_f32_16x16x32_bf16 v[46:49], v[164:167], v[188:191], v[46:49]
	v_mfma_f32_16x16x32_bf16 v[42:45], v[172:175], v[188:191], v[42:45]
	v_mfma_f32_16x16x32_bf16 v[30:33], v[164:167], v[196:199], v[30:33]
	v_mfma_f32_16x16x32_bf16 v[26:29], v[172:175], v[196:199], v[26:29]
	v_mfma_f32_16x16x32_bf16 v[14:17], v[164:167], v[204:207], v[14:17]
	v_mfma_f32_16x16x32_bf16 v[10:13], v[172:175], v[204:207], v[10:13]
	s_setprio 0
	s_barrier
	s_add_u32 s30, s30, 0x40080
	s_addc_u32 s31, s31, 0
	s_mov_b32 m0, s51
	v_lshl_add_u64 v[138:139], s[30:31], 0, v[130:131]
	global_load_lds_dwordx4 v[138:139], off
	v_lshl_add_u64 v[138:139], s[30:31], 0, v[132:133]
	s_mov_b32 m0, s56
	s_nop 0
	global_load_lds_dwordx4 v[138:139], off
	s_waitcnt vmcnt(6)
	s_barrier
	s_setprio 1
	v_mfma_f32_16x16x32_bf16 v[54:57], v[208:211], v[176:179], v[54:57]
	v_mfma_f32_16x16x32_bf16 v[50:53], v[216:219], v[176:179], v[50:53]
	v_mfma_f32_16x16x32_bf16 v[38:41], v[208:211], v[184:187], v[38:41]
	v_mfma_f32_16x16x32_bf16 v[34:37], v[216:219], v[184:187], v[34:37]
	v_mfma_f32_16x16x32_bf16 v[22:25], v[208:211], v[192:195], v[22:25]
	v_mfma_f32_16x16x32_bf16 v[18:21], v[216:219], v[192:195], v[18:21]
	v_mfma_f32_16x16x32_bf16 v[6:9], v[208:211], v[200:203], v[6:9]
	v_mfma_f32_16x16x32_bf16 v[2:5], v[216:219], v[200:203], v[2:5]
	v_mfma_f32_16x16x32_bf16 v[54:57], v[212:215], v[180:183], v[54:57]
	v_mfma_f32_16x16x32_bf16 v[50:53], v[220:223], v[180:183], v[50:53]
	v_mfma_f32_16x16x32_bf16 v[38:41], v[212:215], v[188:191], v[38:41]
	v_mfma_f32_16x16x32_bf16 v[34:37], v[220:223], v[188:191], v[34:37]
	v_mfma_f32_16x16x32_bf16 v[22:25], v[212:215], v[196:199], v[22:25]
	v_mfma_f32_16x16x32_bf16 v[18:21], v[220:223], v[196:199], v[18:21]
	v_mfma_f32_16x16x32_bf16 v[6:9], v[212:215], v[204:207], v[6:9]
	v_mfma_f32_16x16x32_bf16 v[2:5], v[220:223], v[204:207], v[2:5]
	s_setprio 0
	s_add_i32 s64, s64, 2
	s_add_u32 s28, s28, 0x100
	s_addc_u32 s29, s29, 0
	s_add_u32 s62, s62, 0x100
	s_addc_u32 s63, s63, 0
	s_cmp_gt_u32 s64, 13
	s_barrier
	s_cbranch_scc0 .LBB0_750
	v_readlane_b32 s64, v239, 0
	v_readlane_b32 s65, v239, 1
	v_lshl_add_u32 v140, s26, 8, v144
	v_readlane_b32 s66, v239, 2
	v_readlane_b32 s67, v239, 3
	s_mov_b64 s[52:53], s[64:65]
	v_add_u32_e32 v139, 0xffff8000, v140
	v_cmp_gt_i32_e32 vcc, s57, v140
	s_mov_b64 s[54:55], s[66:67]
	v_ashrrev_i32_e32 v141, 31, v140
	v_cndmask_b32_e32 v142, v139, v140, vcc
	v_mov_b32_e32 v139, s55
	v_mov_b32_e32 v163, s53
	v_lshl_or_b32 v138, s24, 8, v146
	v_cndmask_b32_e32 v143, 0, v141, vcc
	v_cndmask_b32_e32 v165, v139, v163, vcc
	v_mov_b32_e32 v139, s54
	v_mov_b32_e32 v163, s52
	v_cndmask_b32_e32 v164, v139, v163, vcc
	v_lshlrev_b64 v[142:143], 12, v[142:143]
	v_ashrrev_i32_e32 v139, 31, v138
	v_lshl_add_u64 v[164:165], v[164:165], 0, v[142:143]
	v_lshlrev_b64 v[142:143], 2, v[138:139]
	v_bfe_u32 v237, v0, 4, 1
	v_mul_u32_u24_e32 v237, 12, v237
	v_add_u32_e32 v138, v138, v237
	v_lshl_add_u64 v[168:169], v[164:165], 0, v[142:143]
	global_load_dwordx4 v[164:167], v[168:169], off
	global_load_dwordx4 v[176:179], v[168:169], off offset:64
	global_load_dwordx4 v[180:183], v[168:169], off offset:512
	global_load_dwordx4 v[184:187], v[168:169], off offset:576
	v_lshlrev_b64 v[170:171], 11, v[140:141]
	v_lshlrev_b64 v[172:173], 12, v[140:141]
	v_lshl_add_u64 v[170:171], s[10:11], 0, v[170:171]
	v_lshl_add_u64 v[172:173], s[86:87], 0, v[172:173]
	v_lshl_add_u64 v[172:173], v[172:173], 0, v[142:143]
	v_lshl_add_u64 v[170:171], v[138:139], 1, v[170:171]
	v_readlane_b32 s68, v239, 4
	v_readlane_b32 s69, v239, 5
	v_readlane_b32 s70, v239, 6
	v_readlane_b32 s71, v239, 7
	v_readlane_b32 s72, v239, 8
	v_readlane_b32 s73, v239, 9
	v_readlane_b32 s74, v239, 10
	v_readlane_b32 s75, v239, 11
	v_readlane_b32 s76, v239, 12
	v_readlane_b32 s77, v239, 13
	v_readlane_b32 s78, v239, 14
	v_readlane_b32 s79, v239, 15
	s_waitcnt vmcnt(0)
;   __device__ __forceinline__ void operator()(const acc8_t& acc, const pg8::Unit& u, int wr, int wc, int fr, int fq) const {
;     ...
;     for (int ai = 0; ai < 2; ai++)
; #pragma unroll
;       for (int m = 0; m < 4; m++) {
;         const int token = (int)EPI_TOKEN(u, ai, m);
;         const float* xr = xrow(p, token);
;         float ss = 0.f;
; #pragma unroll
;         for (int bj = 0; bj < 2; bj++)
; #pragma unroll
;           for (int n = 0; n < 2; n++) {
;             const int f = EPI_COL(u, bj, n);
;             const float4 xv = *(const float4*)(xr + f);
;             const float4 o = make_float4(xv.x + acc[ai][bj][m][n][0], xv.y + acc[ai][bj][m][n][1], xv.z + acc[ai][bj][m][n][2], xv.w + acc[ai][bj][m][n][3]);
;             ss += o.x * o.x + o.y * o.y + o.z * o.z + o.w * o.w;
;             *(float4*)(p.out + O_Y + (size_t)token * 1024 + f) = o;
;             uint2 ob; ob.x = pack2(o.x, o.y); ob.y = pack2(o.z, o.w);
;             *(uint2*)(X1B + (size_t)token * 1024 + f) = ob;
;           }
;         ss = xsum16(ss);
;         ss = xsum32(ss);
;         if (fq == 0) atomicAdd(rss + token, ss);
	v_pk_add_f32 v[126:127], v[126:127], v[164:165]
	v_pk_add_f32 v[128:129], v[128:129], v[166:167]
	v_cvt_pk_bf16_f32 v230, v126, v127
	v_cvt_pk_bf16_f32 v231, v128, v129
	global_store_dwordx4 v[172:173], v[126:129], off
	v_mul_f32_e32 v174, v129, v129
	v_pk_add_f32 v[122:123], v[122:123], v[176:177]
	v_pk_add_f32 v[124:125], v[124:125], v[178:179]
	v_cvt_pk_bf16_f32 v232, v122, v123
	v_cvt_pk_bf16_f32 v233, v124, v125
	global_store_dwordx4 v[172:173], v[122:125], off offset:64
	v_permlane16_swap_b32_e32 v230, v232
	v_permlane16_swap_b32_e32 v231, v233
	global_store_dwordx4 v[170:171], v[230:233], off
	v_pk_add_f32 v[118:119], v[118:119], v[180:181]
	v_pk_add_f32 v[120:121], v[120:121], v[182:183]
	v_cvt_pk_bf16_f32 v234, v118, v119
	v_cvt_pk_bf16_f32 v235, v120, v121
	global_store_dwordx4 v[172:173], v[118:121], off offset:512
	v_mul_f32_e32 v168, v127, v127
	v_pk_fma_f32 v[126:127], v[126:127], v[126:127], v[168:169] op_sel_hi:[1,1,0]
	v_mul_f32_e32 v168, v125, v125
	v_pk_fma_f32 v[126:127], v[128:129], v[128:129], v[126:127]
	v_mul_f32_e32 v128, v123, v123
	v_pk_fma_f32 v[122:123], v[122:123], v[122:123], v[128:129] op_sel_hi:[1,1,0]
	v_pk_add_f32 v[126:127], v[174:175], v[126:127] op_sel_hi:[0,1]
	v_pk_fma_f32 v[122:123], v[124:125], v[124:125], v[122:123]
	v_mul_f32_e32 v124, v119, v119
	v_pk_add_f32 v[122:123], v[168:169], v[122:123] op_sel_hi:[0,1]
	v_pk_fma_f32 v[118:119], v[118:119], v[118:119], v[124:125] op_sel_hi:[1,1,0]
	v_pk_add_f32 v[122:123], v[126:127], v[122:123]
	v_mul_f32_e32 v126, v121, v121
	v_pk_fma_f32 v[118:119], v[120:121], v[120:121], v[118:119]
	v_pk_add_f32 v[114:115], v[114:115], v[184:185]
	v_pk_add_f32 v[116:117], v[116:117], v[186:187]
	v_mul_f32_e32 v120, v115, v115
	v_pk_add_f32 v[118:119], v[126:127], v[118:119] op_sel_hi:[0,1]
	global_store_dwordx4 v[172:173], v[114:117], off offset:576
	v_cvt_pk_bf16_f32 v236, v114, v115
	v_pk_add_f32 v[118:119], v[122:123], v[118:119]
	v_pk_fma_f32 v[114:115], v[114:115], v[114:115], v[120:121] op_sel_hi:[1,1,0]
	v_mul_f32_e32 v122, v117, v117
	v_pk_fma_f32 v[114:115], v[116:117], v[116:117], v[114:115]
	v_cvt_pk_bf16_f32 v237, v116, v117
	v_pk_add_f32 v[114:115], v[122:123], v[114:115] op_sel_hi:[0,1]
	v_pk_add_f32 v[114:115], v[118:119], v[114:115]
	v_permlane16_swap_b32_e32 v234, v236
	v_permlane16_swap_b32_e32 v235, v237
	global_store_dwordx4 v[170:171], v[234:237], off offset:256
	v_mov_b32_e32 v115, v114
	s_nop 1
	v_permlane16_swap_b32_e32 v114, v115
	v_add_f32_e32 v114, v114, v115
	v_mov_b32_e32 v115, v114
	s_nop 1
	v_permlane32_swap_b32_e32 v114, v115
	s_and_saveexec_b64 s[24:25], s[4:5]
	s_cbranch_execz .LBB0_753
	v_add_f32_e32 v116, v114, v115
	v_lshl_add_u64 v[114:115], v[140:141], 2, s[12:13]
	global_atomic_add_f32 v[114:115], v116, off
.LBB0_753:
	s_or_b64 exec, exec, s[24:25]
	v_readlane_b32 s64, v239, 0
	v_readlane_b32 s65, v239, 1
	v_readlane_b32 s66, v239, 2
	v_readlane_b32 s67, v239, 3
	s_mov_b64 s[52:53], s[64:65]
	v_or_b32_e32 v114, 16, v140
	s_mov_b64 s[54:55], s[66:67]
	v_ashrrev_i32_e32 v115, 31, v114
	v_add_u32_e32 v116, 0xffff8010, v140
	v_cmp_gt_i32_e32 vcc, s57, v114
	v_mov_b32_e32 v118, s55
	v_mov_b32_e32 v119, s53
	v_cndmask_b32_e32 v117, 0, v115, vcc
	v_cndmask_b32_e32 v116, v116, v114, vcc
	v_cndmask_b32_e32 v119, v118, v119, vcc
	v_mov_b32_e32 v118, s54
	v_mov_b32_e32 v120, s52
	v_cndmask_b32_e32 v118, v118, v120, vcc
	v_lshlrev_b64 v[116:117], 12, v[116:117]
	v_lshl_add_u64 v[116:117], v[118:119], 0, v[116:117]
	v_lshl_add_u64 v[120:121], v[116:117], 0, v[142:143]
	global_load_dwordx4 v[116:119], v[120:121], off
	global_load_dwordx4 v[176:179], v[120:121], off offset:64
	global_load_dwordx4 v[180:183], v[120:121], off offset:512
	global_load_dwordx4 v[184:187], v[120:121], off offset:576
	v_lshlrev_b64 v[122:123], 11, v[114:115]
	v_lshlrev_b64 v[124:125], 12, v[114:115]
	v_lshl_add_u64 v[122:123], s[10:11], 0, v[122:123]
	v_lshl_add_u64 v[124:125], s[86:87], 0, v[124:125]
	v_lshl_add_u64 v[124:125], v[124:125], 0, v[142:143]
	v_lshl_add_u64 v[122:123], v[138:139], 1, v[122:123]
	v_readlane_b32 s68, v239, 4
	v_readlane_b32 s69, v239, 5
	v_readlane_b32 s70, v239, 6
	v_readlane_b32 s71, v239, 7
	v_readlane_b32 s72, v239, 8
	v_readlane_b32 s73, v239, 9
	v_readlane_b32 s74, v239, 10
	v_readlane_b32 s75, v239, 11
	v_readlane_b32 s76, v239, 12
	v_readlane_b32 s77, v239, 13
	v_readlane_b32 s78, v239, 14
	v_readlane_b32 s79, v239, 15
	s_waitcnt vmcnt(0)
	v_pk_add_f32 v[110:111], v[110:111], v[116:117]
	v_pk_add_f32 v[112:113], v[112:113], v[118:119]
	v_cvt_pk_bf16_f32 v230, v110, v111
	v_cvt_pk_bf16_f32 v231, v112, v113
	global_store_dwordx4 v[124:125], v[110:113], off
	v_mul_f32_e32 v126, v113, v113
	v_pk_add_f32 v[106:107], v[106:107], v[176:177]
	v_pk_add_f32 v[108:109], v[108:109], v[178:179]
	v_cvt_pk_bf16_f32 v232, v106, v107
	v_cvt_pk_bf16_f32 v233, v108, v109
	global_store_dwordx4 v[124:125], v[106:109], off offset:64
	v_permlane16_swap_b32_e32 v230, v232
	v_permlane16_swap_b32_e32 v231, v233
	global_store_dwordx4 v[122:123], v[230:233], off
	v_pk_add_f32 v[102:103], v[102:103], v[180:181]
	v_pk_add_f32 v[104:105], v[104:105], v[182:183]
	v_cvt_pk_bf16_f32 v234, v102, v103
	v_cvt_pk_bf16_f32 v235, v104, v105
	global_store_dwordx4 v[124:125], v[102:105], off offset:512
	v_mul_f32_e32 v120, v111, v111
	v_pk_fma_f32 v[110:111], v[110:111], v[110:111], v[120:121] op_sel_hi:[1,1,0]
	v_mul_f32_e32 v120, v109, v109
	v_pk_fma_f32 v[110:111], v[112:113], v[112:113], v[110:111]
	v_mul_f32_e32 v112, v107, v107
	v_pk_fma_f32 v[106:107], v[106:107], v[106:107], v[112:113] op_sel_hi:[1,1,0]
	v_pk_add_f32 v[110:111], v[126:127], v[110:111] op_sel_hi:[0,1]
	v_pk_fma_f32 v[106:107], v[108:109], v[108:109], v[106:107]
	v_mul_f32_e32 v108, v103, v103
	v_pk_add_f32 v[106:107], v[120:121], v[106:107] op_sel_hi:[0,1]
	v_pk_fma_f32 v[102:103], v[102:103], v[102:103], v[108:109] op_sel_hi:[1,1,0]
	v_pk_add_f32 v[106:107], v[110:111], v[106:107]
	v_mul_f32_e32 v110, v105, v105
	v_pk_fma_f32 v[102:103], v[104:105], v[104:105], v[102:103]
	v_pk_add_f32 v[98:99], v[98:99], v[184:185]
	v_pk_add_f32 v[100:101], v[100:101], v[186:187]
	v_mul_f32_e32 v104, v99, v99
	v_pk_add_f32 v[102:103], v[110:111], v[102:103] op_sel_hi:[0,1]
	global_store_dwordx4 v[124:125], v[98:101], off offset:576
	v_cvt_pk_bf16_f32 v236, v98, v99
	v_pk_add_f32 v[102:103], v[106:107], v[102:103]
	v_pk_fma_f32 v[98:99], v[98:99], v[98:99], v[104:105] op_sel_hi:[1,1,0]
	v_mul_f32_e32 v106, v101, v101
	v_pk_fma_f32 v[98:99], v[100:101], v[100:101], v[98:99]
	v_cvt_pk_bf16_f32 v237, v100, v101
	v_pk_add_f32 v[98:99], v[106:107], v[98:99] op_sel_hi:[0,1]
	v_pk_add_f32 v[98:99], v[102:103], v[98:99]
	v_permlane16_swap_b32_e32 v234, v236
	v_permlane16_swap_b32_e32 v235, v237
	global_store_dwordx4 v[122:123], v[234:237], off offset:256
	v_mov_b32_e32 v99, v98
	s_nop 1
	v_permlane16_swap_b32_e32 v98, v99
	v_add_f32_e32 v98, v98, v99
	v_mov_b32_e32 v99, v98
	s_nop 1
	v_permlane32_swap_b32_e32 v98, v99
	s_and_saveexec_b64 s[24:25], s[4:5]
	s_cbranch_execz .LBB0_755
;   __device__ __forceinline__ void operator()(const acc8_t& acc, const pg8::Unit& u, int wr, int wc, int fr, int fq) const {
;     ...
;     for (int ai = 0; ai < 2; ai++)
; #pragma unroll
;       for (int m = 0; m < 4; m++) {
;         const int token = (int)EPI_TOKEN(u, ai, m);
;         const float* xr = xrow(p, token);
;         float ss = 0.f;
; #pragma unroll
;         for (int bj = 0; bj < 2; bj++)
; #pragma unroll
;           for (int n = 0; n < 2; n++) {
;             const int f = EPI_COL(u, bj, n);
;             const float4 xv = *(const float4*)(xr + f);
;             const float4 o = make_float4(xv.x + acc[ai][bj][m][n][0], xv.y + acc[ai][bj][m][n][1], xv.z + acc[ai][bj][m][n][2], xv.w + acc[ai][bj][m][n][3]);
;             ss += o.x * o.x + o.y * o.y + o.z * o.z + o.w * o.w;
;             *(float4*)(p.out + O_Y + (size_t)token * 1024 + f) = o;
;             uint2 ob; ob.x = pack2(o.x, o.y); ob.y = pack2(o.z, o.w);
;             *(uint2*)(X1B + (size_t)token * 1024 + f) = ob;
;           }
;         ss = xsum16(ss);
;         ss = xsum32(ss);
;         if (fq == 0) atomicAdd(rss + token, ss);
	v_add_f32_e32 v100, v98, v99
	v_lshl_add_u64 v[98:99], v[114:115], 2, s[12:13]
	global_atomic_add_f32 v[98:99], v100, off
.LBB0_755:
	s_or_b64 exec, exec, s[24:25]
	v_readlane_b32 s64, v239, 0
	v_readlane_b32 s65, v239, 1
	v_readlane_b32 s66, v239, 2
	v_readlane_b32 s67, v239, 3
	s_mov_b64 s[52:53], s[64:65]
	v_or_b32_e32 v98, 32, v140
	s_mov_b64 s[54:55], s[66:67]
	v_ashrrev_i32_e32 v99, 31, v98
	v_add_u32_e32 v100, 0xffff8020, v140
	v_cmp_gt_i32_e32 vcc, s57, v98
	v_mov_b32_e32 v102, s55
	v_mov_b32_e32 v103, s53
	v_cndmask_b32_e32 v101, 0, v99, vcc
	v_cndmask_b32_e32 v100, v100, v98, vcc
	v_cndmask_b32_e32 v103, v102, v103, vcc
	v_mov_b32_e32 v102, s54
	v_mov_b32_e32 v104, s52
	v_cndmask_b32_e32 v102, v102, v104, vcc
	v_lshlrev_b64 v[100:101], 12, v[100:101]
	v_lshl_add_u64 v[100:101], v[102:103], 0, v[100:101]
	v_lshl_add_u64 v[104:105], v[100:101], 0, v[142:143]
	global_load_dwordx4 v[100:103], v[104:105], off
	global_load_dwordx4 v[176:179], v[104:105], off offset:64
	global_load_dwordx4 v[180:183], v[104:105], off offset:512
	global_load_dwordx4 v[184:187], v[104:105], off offset:576
	v_lshlrev_b64 v[106:107], 11, v[98:99]
	v_lshlrev_b64 v[108:109], 12, v[98:99]
	v_lshl_add_u64 v[106:107], s[10:11], 0, v[106:107]
	v_lshl_add_u64 v[108:109], s[86:87], 0, v[108:109]
	v_lshl_add_u64 v[108:109], v[108:109], 0, v[142:143]
	v_lshl_add_u64 v[106:107], v[138:139], 1, v[106:107]
	v_readlane_b32 s68, v239, 4
	v_readlane_b32 s69, v239, 5
	v_readlane_b32 s70, v239, 6
	v_readlane_b32 s71, v239, 7
	v_readlane_b32 s72, v239, 8
	v_readlane_b32 s73, v239, 9
	v_readlane_b32 s74, v239, 10
	v_readlane_b32 s75, v239, 11
	v_readlane_b32 s76, v239, 12
	v_readlane_b32 s77, v239, 13
	v_readlane_b32 s78, v239, 14
	v_readlane_b32 s79, v239, 15
	s_waitcnt vmcnt(0)
	v_pk_add_f32 v[94:95], v[94:95], v[100:101]
	v_pk_add_f32 v[96:97], v[96:97], v[102:103]
	v_cvt_pk_bf16_f32 v230, v94, v95
	v_cvt_pk_bf16_f32 v231, v96, v97
	global_store_dwordx4 v[108:109], v[94:97], off
	v_mul_f32_e32 v110, v97, v97
	v_pk_add_f32 v[90:91], v[90:91], v[176:177]
	v_pk_add_f32 v[92:93], v[92:93], v[178:179]
	v_cvt_pk_bf16_f32 v232, v90, v91
	v_cvt_pk_bf16_f32 v233, v92, v93
	global_store_dwordx4 v[108:109], v[90:93], off offset:64
	v_permlane16_swap_b32_e32 v230, v232
	v_permlane16_swap_b32_e32 v231, v233
	global_store_dwordx4 v[106:107], v[230:233], off
	v_pk_add_f32 v[86:87], v[86:87], v[180:181]
	v_pk_add_f32 v[88:89], v[88:89], v[182:183]
	v_cvt_pk_bf16_f32 v234, v86, v87
	v_cvt_pk_bf16_f32 v235, v88, v89
	global_store_dwordx4 v[108:109], v[86:89], off offset:512
	v_mul_f32_e32 v104, v95, v95
	v_pk_fma_f32 v[94:95], v[94:95], v[94:95], v[104:105] op_sel_hi:[1,1,0]
	v_mul_f32_e32 v104, v93, v93
	v_pk_fma_f32 v[94:95], v[96:97], v[96:97], v[94:95]
	v_mul_f32_e32 v96, v91, v91
	v_pk_fma_f32 v[90:91], v[90:91], v[90:91], v[96:97] op_sel_hi:[1,1,0]
	v_pk_add_f32 v[94:95], v[110:111], v[94:95] op_sel_hi:[0,1]
	v_pk_fma_f32 v[90:91], v[92:93], v[92:93], v[90:91]
	v_mul_f32_e32 v92, v87, v87
	v_pk_add_f32 v[90:91], v[104:105], v[90:91] op_sel_hi:[0,1]
	v_pk_fma_f32 v[86:87], v[86:87], v[86:87], v[92:93] op_sel_hi:[1,1,0]
	v_pk_add_f32 v[90:91], v[94:95], v[90:91]
	v_mul_f32_e32 v94, v89, v89
	v_pk_fma_f32 v[86:87], v[88:89], v[88:89], v[86:87]
	v_pk_add_f32 v[82:83], v[82:83], v[184:185]
	v_pk_add_f32 v[84:85], v[84:85], v[186:187]
	v_mul_f32_e32 v88, v83, v83
	v_pk_add_f32 v[86:87], v[94:95], v[86:87] op_sel_hi:[0,1]
	global_store_dwordx4 v[108:109], v[82:85], off offset:576
	v_cvt_pk_bf16_f32 v236, v82, v83
	v_pk_add_f32 v[86:87], v[90:91], v[86:87]
	v_pk_fma_f32 v[82:83], v[82:83], v[82:83], v[88:89] op_sel_hi:[1,1,0]
	v_mul_f32_e32 v90, v85, v85
	v_pk_fma_f32 v[82:83], v[84:85], v[84:85], v[82:83]
	v_cvt_pk_bf16_f32 v237, v84, v85
	v_pk_add_f32 v[82:83], v[90:91], v[82:83] op_sel_hi:[0,1]
	v_pk_add_f32 v[82:83], v[86:87], v[82:83]
	v_permlane16_swap_b32_e32 v234, v236
	v_permlane16_swap_b32_e32 v235, v237
	global_store_dwordx4 v[106:107], v[234:237], off offset:256
	v_mov_b32_e32 v83, v82
	s_nop 1
	v_permlane16_swap_b32_e32 v82, v83
	v_add_f32_e32 v82, v82, v83
	v_mov_b32_e32 v83, v82
	s_nop 1
	v_permlane32_swap_b32_e32 v82, v83
	s_and_saveexec_b64 s[24:25], s[4:5]
	s_cbranch_execz .LBB0_757
	v_add_f32_e32 v84, v82, v83
	v_lshl_add_u64 v[82:83], v[98:99], 2, s[12:13]
	global_atomic_add_f32 v[82:83], v84, off
;   __device__ __forceinline__ void operator()(const acc8_t& acc, const pg8::Unit& u, int wr, int wc, int fr, int fq) const {
;     ...
;     for (int ai = 0; ai < 2; ai++)
; #pragma unroll
;       for (int m = 0; m < 4; m++) {
;         const int token = (int)EPI_TOKEN(u, ai, m);
;         const float* xr = xrow(p, token);
;         float ss = 0.f;
; #pragma unroll
;         for (int bj = 0; bj < 2; bj++)
; #pragma unroll
;           for (int n = 0; n < 2; n++) {
;             const int f = EPI_COL(u, bj, n);
;             const float4 xv = *(const float4*)(xr + f);
;             const float4 o = make_float4(xv.x + acc[ai][bj][m][n][0], xv.y + acc[ai][bj][m][n][1], xv.z + acc[ai][bj][m][n][2], xv.w + acc[ai][bj][m][n][3]);
;             ss += o.x * o.x + o.y * o.y + o.z * o.z + o.w * o.w;
;             *(float4*)(p.out + O_Y + (size_t)token * 1024 + f) = o;
;             uint2 ob; ob.x = pack2(o.x, o.y); ob.y = pack2(o.z, o.w);
;             *(uint2*)(X1B + (size_t)token * 1024 + f) = ob;
;           }
;         ss = xsum16(ss);
;         ss = xsum32(ss);
;         if (fq == 0) atomicAdd(rss + token, ss);
.LBB0_757:
	s_or_b64 exec, exec, s[24:25]
	v_readlane_b32 s64, v239, 0
	v_readlane_b32 s65, v239, 1
	v_readlane_b32 s66, v239, 2
	v_readlane_b32 s67, v239, 3
	s_mov_b64 s[52:53], s[64:65]
	v_or_b32_e32 v82, 48, v140
	s_mov_b64 s[54:55], s[66:67]
	v_ashrrev_i32_e32 v83, 31, v82
	v_add_u32_e32 v84, 0xffff8030, v140
	v_cmp_gt_i32_e32 vcc, s57, v82
	v_mov_b32_e32 v86, s55
	v_mov_b32_e32 v87, s53
	v_cndmask_b32_e32 v85, 0, v83, vcc
	v_cndmask_b32_e32 v84, v84, v82, vcc
	v_cndmask_b32_e32 v87, v86, v87, vcc
	v_mov_b32_e32 v86, s54
	v_mov_b32_e32 v88, s52
	v_cndmask_b32_e32 v86, v86, v88, vcc
	v_lshlrev_b64 v[84:85], 12, v[84:85]
	v_lshl_add_u64 v[84:85], v[86:87], 0, v[84:85]
	v_lshl_add_u64 v[88:89], v[84:85], 0, v[142:143]
	global_load_dwordx4 v[84:87], v[88:89], off
	global_load_dwordx4 v[176:179], v[88:89], off offset:64
	global_load_dwordx4 v[180:183], v[88:89], off offset:512
	global_load_dwordx4 v[184:187], v[88:89], off offset:576
	v_lshlrev_b64 v[90:91], 11, v[82:83]
	v_lshlrev_b64 v[92:93], 12, v[82:83]
	v_lshl_add_u64 v[90:91], s[10:11], 0, v[90:91]
	v_lshl_add_u64 v[92:93], s[86:87], 0, v[92:93]
	v_lshl_add_u64 v[92:93], v[92:93], 0, v[142:143]
	v_lshl_add_u64 v[90:91], v[138:139], 1, v[90:91]
	v_readlane_b32 s68, v239, 4
	v_readlane_b32 s69, v239, 5
	v_readlane_b32 s70, v239, 6
	v_readlane_b32 s71, v239, 7
	v_readlane_b32 s72, v239, 8
	v_readlane_b32 s73, v239, 9
	v_readlane_b32 s74, v239, 10
	v_readlane_b32 s75, v239, 11
	v_readlane_b32 s76, v239, 12
	v_readlane_b32 s77, v239, 13
	v_readlane_b32 s78, v239, 14
	v_readlane_b32 s79, v239, 15
	s_waitcnt vmcnt(0)
	v_pk_add_f32 v[78:79], v[78:79], v[84:85]
	v_pk_add_f32 v[80:81], v[80:81], v[86:87]
	v_cvt_pk_bf16_f32 v230, v78, v79
	v_cvt_pk_bf16_f32 v231, v80, v81
	global_store_dwordx4 v[92:93], v[78:81], off
	v_mul_f32_e32 v94, v81, v81
	v_pk_add_f32 v[74:75], v[74:75], v[176:177]
	v_pk_add_f32 v[76:77], v[76:77], v[178:179]
	v_cvt_pk_bf16_f32 v232, v74, v75
	v_cvt_pk_bf16_f32 v233, v76, v77
	global_store_dwordx4 v[92:93], v[74:77], off offset:64
	v_permlane16_swap_b32_e32 v230, v232
	v_permlane16_swap_b32_e32 v231, v233
	global_store_dwordx4 v[90:91], v[230:233], off
	v_pk_add_f32 v[70:71], v[70:71], v[180:181]
	v_pk_add_f32 v[72:73], v[72:73], v[182:183]
	v_cvt_pk_bf16_f32 v234, v70, v71
	v_cvt_pk_bf16_f32 v235, v72, v73
	global_store_dwordx4 v[92:93], v[70:73], off offset:512
	v_mul_f32_e32 v88, v79, v79
	v_pk_fma_f32 v[78:79], v[78:79], v[78:79], v[88:89] op_sel_hi:[1,1,0]
	v_mul_f32_e32 v88, v77, v77
	v_pk_fma_f32 v[78:79], v[80:81], v[80:81], v[78:79]
	v_mul_f32_e32 v80, v75, v75
	v_pk_fma_f32 v[74:75], v[74:75], v[74:75], v[80:81] op_sel_hi:[1,1,0]
	v_pk_add_f32 v[78:79], v[94:95], v[78:79] op_sel_hi:[0,1]
	v_pk_fma_f32 v[74:75], v[76:77], v[76:77], v[74:75]
	v_mul_f32_e32 v76, v71, v71
	v_pk_add_f32 v[74:75], v[88:89], v[74:75] op_sel_hi:[0,1]
	v_pk_fma_f32 v[70:71], v[70:71], v[70:71], v[76:77] op_sel_hi:[1,1,0]
	v_pk_add_f32 v[74:75], v[78:79], v[74:75]
	v_mul_f32_e32 v78, v73, v73
	v_pk_fma_f32 v[70:71], v[72:73], v[72:73], v[70:71]
	v_pk_add_f32 v[66:67], v[66:67], v[184:185]
	v_pk_add_f32 v[68:69], v[68:69], v[186:187]
	v_mul_f32_e32 v72, v67, v67
	v_pk_add_f32 v[70:71], v[78:79], v[70:71] op_sel_hi:[0,1]
	global_store_dwordx4 v[92:93], v[66:69], off offset:576
	v_cvt_pk_bf16_f32 v236, v66, v67
	v_pk_add_f32 v[70:71], v[74:75], v[70:71]
	v_pk_fma_f32 v[66:67], v[66:67], v[66:67], v[72:73] op_sel_hi:[1,1,0]
	v_mul_f32_e32 v74, v69, v69
	v_pk_fma_f32 v[66:67], v[68:69], v[68:69], v[66:67]
	v_cvt_pk_bf16_f32 v237, v68, v69
	v_pk_add_f32 v[66:67], v[74:75], v[66:67] op_sel_hi:[0,1]
	v_pk_add_f32 v[66:67], v[70:71], v[66:67]
	v_permlane16_swap_b32_e32 v234, v236
	v_permlane16_swap_b32_e32 v235, v237
	global_store_dwordx4 v[90:91], v[234:237], off offset:256
	v_mov_b32_e32 v67, v66
	s_nop 1
	v_permlane16_swap_b32_e32 v66, v67
	v_add_f32_e32 v66, v66, v67
	v_mov_b32_e32 v67, v66
	s_nop 1
	v_permlane32_swap_b32_e32 v66, v67
	s_and_saveexec_b64 s[24:25], s[4:5]
	s_cbranch_execz .LBB0_759
	v_add_f32_e32 v68, v66, v67
	v_lshl_add_u64 v[66:67], v[82:83], 2, s[12:13]
	global_atomic_add_f32 v[66:67], v68, off
.LBB0_759:
	s_or_b64 exec, exec, s[24:25]
	v_readlane_b32 s64, v239, 0
	v_readlane_b32 s65, v239, 1
	v_readlane_b32 s66, v239, 2
	v_readlane_b32 s67, v239, 3
	s_mov_b64 s[52:53], s[64:65]
	v_add_u32_e32 v66, 0x80, v140
	s_mov_b64 s[54:55], s[66:67]
	v_ashrrev_i32_e32 v67, 31, v66
	v_add_u32_e32 v68, 0xffff8080, v140
	v_cmp_gt_i32_e32 vcc, s57, v66
	v_mov_b32_e32 v70, s55
	v_mov_b32_e32 v71, s53
	v_cndmask_b32_e32 v69, 0, v67, vcc
	v_cndmask_b32_e32 v68, v68, v66, vcc
	v_cndmask_b32_e32 v71, v70, v71, vcc
	v_mov_b32_e32 v70, s54
	v_mov_b32_e32 v72, s52
	v_cndmask_b32_e32 v70, v70, v72, vcc
	v_lshlrev_b64 v[68:69], 12, v[68:69]
	v_lshl_add_u64 v[68:69], v[70:71], 0, v[68:69]
	v_lshl_add_u64 v[72:73], v[68:69], 0, v[142:143]
	global_load_dwordx4 v[68:71], v[72:73], off
	global_load_dwordx4 v[176:179], v[72:73], off offset:64
	global_load_dwordx4 v[180:183], v[72:73], off offset:512
	global_load_dwordx4 v[184:187], v[72:73], off offset:576
	v_lshlrev_b64 v[74:75], 11, v[66:67]
	v_lshlrev_b64 v[76:77], 12, v[66:67]
	v_lshl_add_u64 v[74:75], s[10:11], 0, v[74:75]
	v_lshl_add_u64 v[76:77], s[86:87], 0, v[76:77]
	v_lshl_add_u64 v[76:77], v[76:77], 0, v[142:143]
	v_lshl_add_u64 v[74:75], v[138:139], 1, v[74:75]
	v_readlane_b32 s68, v239, 4
	v_readlane_b32 s69, v239, 5
	v_readlane_b32 s70, v239, 6
	v_readlane_b32 s71, v239, 7
	v_readlane_b32 s72, v239, 8
	v_readlane_b32 s73, v239, 9
	v_readlane_b32 s74, v239, 10
	v_readlane_b32 s75, v239, 11
	v_readlane_b32 s76, v239, 12
	v_readlane_b32 s77, v239, 13
	v_readlane_b32 s78, v239, 14
	v_readlane_b32 s79, v239, 15
	s_waitcnt vmcnt(0)
;   __device__ __forceinline__ void operator()(const acc8_t& acc, const pg8::Unit& u, int wr, int wc, int fr, int fq) const {
;     ...
;     for (int ai = 0; ai < 2; ai++)
; #pragma unroll
;       for (int m = 0; m < 4; m++) {
;         const int token = (int)EPI_TOKEN(u, ai, m);
;         const float* xr = xrow(p, token);
;         float ss = 0.f;
; #pragma unroll
;         for (int bj = 0; bj < 2; bj++)
; #pragma unroll
;           for (int n = 0; n < 2; n++) {
;             const int f = EPI_COL(u, bj, n);
;             const float4 xv = *(const float4*)(xr + f);
;             const float4 o = make_float4(xv.x + acc[ai][bj][m][n][0], xv.y + acc[ai][bj][m][n][1], xv.z + acc[ai][bj][m][n][2], xv.w + acc[ai][bj][m][n][3]);
;             ss += o.x * o.x + o.y * o.y + o.z * o.z + o.w * o.w;
;             *(float4*)(p.out + O_Y + (size_t)token * 1024 + f) = o;
;             uint2 ob; ob.x = pack2(o.x, o.y); ob.y = pack2(o.z, o.w);
;             *(uint2*)(X1B + (size_t)token * 1024 + f) = ob;
;           }
;         ss = xsum16(ss);
;         ss = xsum32(ss);
;         if (fq == 0) atomicAdd(rss + token, ss);
	v_pk_add_f32 v[62:63], v[62:63], v[68:69]
	v_pk_add_f32 v[64:65], v[64:65], v[70:71]
	v_cvt_pk_bf16_f32 v230, v62, v63
	v_cvt_pk_bf16_f32 v231, v64, v65
	global_store_dwordx4 v[76:77], v[62:65], off
	v_mul_f32_e32 v78, v65, v65
	v_pk_add_f32 v[58:59], v[58:59], v[176:177]
	v_pk_add_f32 v[60:61], v[60:61], v[178:179]
	v_cvt_pk_bf16_f32 v232, v58, v59
	v_cvt_pk_bf16_f32 v233, v60, v61
	global_store_dwordx4 v[76:77], v[58:61], off offset:64
	v_permlane16_swap_b32_e32 v230, v232
	v_permlane16_swap_b32_e32 v231, v233
	global_store_dwordx4 v[74:75], v[230:233], off
	v_pk_add_f32 v[54:55], v[54:55], v[180:181]
	v_pk_add_f32 v[56:57], v[56:57], v[182:183]
	v_cvt_pk_bf16_f32 v234, v54, v55
	v_cvt_pk_bf16_f32 v235, v56, v57
	global_store_dwordx4 v[76:77], v[54:57], off offset:512
	v_mul_f32_e32 v72, v63, v63
	v_pk_fma_f32 v[62:63], v[62:63], v[62:63], v[72:73] op_sel_hi:[1,1,0]
	v_mul_f32_e32 v72, v61, v61
	v_pk_fma_f32 v[62:63], v[64:65], v[64:65], v[62:63]
	v_mul_f32_e32 v64, v59, v59
	v_pk_fma_f32 v[58:59], v[58:59], v[58:59], v[64:65] op_sel_hi:[1,1,0]
	v_pk_add_f32 v[62:63], v[78:79], v[62:63] op_sel_hi:[0,1]
	v_pk_fma_f32 v[58:59], v[60:61], v[60:61], v[58:59]
	v_mul_f32_e32 v60, v55, v55
	v_pk_add_f32 v[58:59], v[72:73], v[58:59] op_sel_hi:[0,1]
	v_pk_fma_f32 v[54:55], v[54:55], v[54:55], v[60:61] op_sel_hi:[1,1,0]
	v_pk_add_f32 v[58:59], v[62:63], v[58:59]
	v_mul_f32_e32 v62, v57, v57
	v_pk_fma_f32 v[54:55], v[56:57], v[56:57], v[54:55]
	v_pk_add_f32 v[50:51], v[50:51], v[184:185]
	v_pk_add_f32 v[52:53], v[52:53], v[186:187]
	v_mul_f32_e32 v56, v51, v51
	v_pk_add_f32 v[54:55], v[62:63], v[54:55] op_sel_hi:[0,1]
	global_store_dwordx4 v[76:77], v[50:53], off offset:576
	v_cvt_pk_bf16_f32 v236, v50, v51
	v_pk_add_f32 v[54:55], v[58:59], v[54:55]
	v_pk_fma_f32 v[50:51], v[50:51], v[50:51], v[56:57] op_sel_hi:[1,1,0]
	v_mul_f32_e32 v58, v53, v53
	v_pk_fma_f32 v[50:51], v[52:53], v[52:53], v[50:51]
	v_cvt_pk_bf16_f32 v237, v52, v53
	v_pk_add_f32 v[50:51], v[58:59], v[50:51] op_sel_hi:[0,1]
	v_pk_add_f32 v[50:51], v[54:55], v[50:51]
	v_permlane16_swap_b32_e32 v234, v236
	v_permlane16_swap_b32_e32 v235, v237
	global_store_dwordx4 v[74:75], v[234:237], off offset:256
	v_mov_b32_e32 v51, v50
	s_nop 1
	v_permlane16_swap_b32_e32 v50, v51
	v_add_f32_e32 v50, v50, v51
	v_mov_b32_e32 v51, v50
	s_nop 1
	v_permlane32_swap_b32_e32 v50, v51
	s_and_saveexec_b64 s[24:25], s[4:5]
	s_cbranch_execz .LBB0_761
	v_add_f32_e32 v52, v50, v51
	v_lshl_add_u64 v[50:51], v[66:67], 2, s[12:13]
	global_atomic_add_f32 v[50:51], v52, off
.LBB0_761:
	s_or_b64 exec, exec, s[24:25]
	v_readlane_b32 s64, v239, 0
	v_readlane_b32 s65, v239, 1
	v_readlane_b32 s66, v239, 2
	v_readlane_b32 s67, v239, 3
	s_mov_b64 s[52:53], s[64:65]
	v_add_u32_e32 v50, 0x90, v140
	s_mov_b64 s[54:55], s[66:67]
	v_ashrrev_i32_e32 v51, 31, v50
	v_add_u32_e32 v52, 0xffff8090, v140
	v_cmp_gt_i32_e32 vcc, s57, v50
	v_mov_b32_e32 v54, s55
	v_mov_b32_e32 v55, s53
	v_cndmask_b32_e32 v53, 0, v51, vcc
	v_cndmask_b32_e32 v52, v52, v50, vcc
	v_cndmask_b32_e32 v55, v54, v55, vcc
	v_mov_b32_e32 v54, s54
	v_mov_b32_e32 v56, s52
	v_cndmask_b32_e32 v54, v54, v56, vcc
	v_lshlrev_b64 v[52:53], 12, v[52:53]
	v_lshl_add_u64 v[52:53], v[54:55], 0, v[52:53]
	v_lshl_add_u64 v[56:57], v[52:53], 0, v[142:143]
	global_load_dwordx4 v[52:55], v[56:57], off
	global_load_dwordx4 v[176:179], v[56:57], off offset:64
	global_load_dwordx4 v[180:183], v[56:57], off offset:512
	global_load_dwordx4 v[184:187], v[56:57], off offset:576
	v_lshlrev_b64 v[58:59], 11, v[50:51]
	v_lshlrev_b64 v[60:61], 12, v[50:51]
	v_lshl_add_u64 v[58:59], s[10:11], 0, v[58:59]
	v_lshl_add_u64 v[60:61], s[86:87], 0, v[60:61]
	v_lshl_add_u64 v[60:61], v[60:61], 0, v[142:143]
	v_lshl_add_u64 v[58:59], v[138:139], 1, v[58:59]
	v_readlane_b32 s68, v239, 4
	v_readlane_b32 s69, v239, 5
	v_readlane_b32 s70, v239, 6
	v_readlane_b32 s71, v239, 7
	v_readlane_b32 s72, v239, 8
	v_readlane_b32 s73, v239, 9
	v_readlane_b32 s74, v239, 10
	v_readlane_b32 s75, v239, 11
	v_readlane_b32 s76, v239, 12
	v_readlane_b32 s77, v239, 13
	v_readlane_b32 s78, v239, 14
	v_readlane_b32 s79, v239, 15
	s_waitcnt vmcnt(0)
	v_pk_add_f32 v[46:47], v[46:47], v[52:53]
	v_pk_add_f32 v[48:49], v[48:49], v[54:55]
	v_cvt_pk_bf16_f32 v230, v46, v47
	v_cvt_pk_bf16_f32 v231, v48, v49
	global_store_dwordx4 v[60:61], v[46:49], off
	v_mul_f32_e32 v62, v49, v49
	v_pk_add_f32 v[42:43], v[42:43], v[176:177]
	v_pk_add_f32 v[44:45], v[44:45], v[178:179]
	v_cvt_pk_bf16_f32 v232, v42, v43
	v_cvt_pk_bf16_f32 v233, v44, v45
	global_store_dwordx4 v[60:61], v[42:45], off offset:64
	v_permlane16_swap_b32_e32 v230, v232
	v_permlane16_swap_b32_e32 v231, v233
	global_store_dwordx4 v[58:59], v[230:233], off
	v_pk_add_f32 v[38:39], v[38:39], v[180:181]
	v_pk_add_f32 v[40:41], v[40:41], v[182:183]
	v_cvt_pk_bf16_f32 v234, v38, v39
	v_cvt_pk_bf16_f32 v235, v40, v41
	global_store_dwordx4 v[60:61], v[38:41], off offset:512
	v_mul_f32_e32 v56, v47, v47
	v_pk_fma_f32 v[46:47], v[46:47], v[46:47], v[56:57] op_sel_hi:[1,1,0]
	v_mul_f32_e32 v56, v45, v45
	v_pk_fma_f32 v[46:47], v[48:49], v[48:49], v[46:47]
	v_mul_f32_e32 v48, v43, v43
	v_pk_fma_f32 v[42:43], v[42:43], v[42:43], v[48:49] op_sel_hi:[1,1,0]
	v_pk_add_f32 v[46:47], v[62:63], v[46:47] op_sel_hi:[0,1]
	v_pk_fma_f32 v[42:43], v[44:45], v[44:45], v[42:43]
	v_mul_f32_e32 v44, v39, v39
	v_pk_add_f32 v[42:43], v[56:57], v[42:43] op_sel_hi:[0,1]
	v_pk_fma_f32 v[38:39], v[38:39], v[38:39], v[44:45] op_sel_hi:[1,1,0]
	v_pk_add_f32 v[42:43], v[46:47], v[42:43]
	v_mul_f32_e32 v46, v41, v41
	v_pk_fma_f32 v[38:39], v[40:41], v[40:41], v[38:39]
	v_pk_add_f32 v[34:35], v[34:35], v[184:185]
	v_pk_add_f32 v[36:37], v[36:37], v[186:187]
	v_mul_f32_e32 v40, v35, v35
	v_pk_add_f32 v[38:39], v[46:47], v[38:39] op_sel_hi:[0,1]
	global_store_dwordx4 v[60:61], v[34:37], off offset:576
	v_cvt_pk_bf16_f32 v236, v34, v35
	v_pk_add_f32 v[38:39], v[42:43], v[38:39]
	v_pk_fma_f32 v[34:35], v[34:35], v[34:35], v[40:41] op_sel_hi:[1,1,0]
	v_mul_f32_e32 v42, v37, v37
	v_pk_fma_f32 v[34:35], v[36:37], v[36:37], v[34:35]
	v_cvt_pk_bf16_f32 v237, v36, v37
	v_pk_add_f32 v[34:35], v[42:43], v[34:35] op_sel_hi:[0,1]
	v_pk_add_f32 v[34:35], v[38:39], v[34:35]
	v_permlane16_swap_b32_e32 v234, v236
	v_permlane16_swap_b32_e32 v235, v237
	global_store_dwordx4 v[58:59], v[234:237], off offset:256
	v_mov_b32_e32 v35, v34
	s_nop 1
	v_permlane16_swap_b32_e32 v34, v35
	v_add_f32_e32 v34, v34, v35
	v_mov_b32_e32 v35, v34
	s_nop 1
	v_permlane32_swap_b32_e32 v34, v35
	s_and_saveexec_b64 s[24:25], s[4:5]
	s_cbranch_execz .LBB0_763
	v_add_f32_e32 v36, v34, v35
	v_lshl_add_u64 v[34:35], v[50:51], 2, s[12:13]
	global_atomic_add_f32 v[34:35], v36, off
;   __device__ __forceinline__ void operator()(const acc8_t& acc, const pg8::Unit& u, int wr, int wc, int fr, int fq) const {
;     ...
;     for (int ai = 0; ai < 2; ai++)
; #pragma unroll
;       for (int m = 0; m < 4; m++) {
;         const int token = (int)EPI_TOKEN(u, ai, m);
;         const float* xr = xrow(p, token);
;         float ss = 0.f;
; #pragma unroll
;         for (int bj = 0; bj < 2; bj++)
; #pragma unroll
;           for (int n = 0; n < 2; n++) {
;             const int f = EPI_COL(u, bj, n);
;             const float4 xv = *(const float4*)(xr + f);
;             const float4 o = make_float4(xv.x + acc[ai][bj][m][n][0], xv.y + acc[ai][bj][m][n][1], xv.z + acc[ai][bj][m][n][2], xv.w + acc[ai][bj][m][n][3]);
;             ss += o.x * o.x + o.y * o.y + o.z * o.z + o.w * o.w;
;             *(float4*)(p.out + O_Y + (size_t)token * 1024 + f) = o;
;             uint2 ob; ob.x = pack2(o.x, o.y); ob.y = pack2(o.z, o.w);
;             *(uint2*)(X1B + (size_t)token * 1024 + f) = ob;
;           }
;         ss = xsum16(ss);
;         ss = xsum32(ss);
;         if (fq == 0) atomicAdd(rss + token, ss);
.LBB0_763:
	s_or_b64 exec, exec, s[24:25]
	v_readlane_b32 s64, v239, 0
	v_readlane_b32 s65, v239, 1
	v_readlane_b32 s66, v239, 2
	v_readlane_b32 s67, v239, 3
	s_mov_b64 s[52:53], s[64:65]
	v_add_u32_e32 v34, 0xa0, v140
	s_mov_b64 s[54:55], s[66:67]
	v_ashrrev_i32_e32 v35, 31, v34
	v_add_u32_e32 v36, 0xffff80a0, v140
	v_cmp_gt_i32_e32 vcc, s57, v34
	v_mov_b32_e32 v38, s55
	v_mov_b32_e32 v39, s53
	v_cndmask_b32_e32 v37, 0, v35, vcc
	v_cndmask_b32_e32 v36, v36, v34, vcc
	v_cndmask_b32_e32 v39, v38, v39, vcc
	v_mov_b32_e32 v38, s54
	v_mov_b32_e32 v40, s52
	v_cndmask_b32_e32 v38, v38, v40, vcc
	v_lshlrev_b64 v[36:37], 12, v[36:37]
	v_lshl_add_u64 v[36:37], v[38:39], 0, v[36:37]
	v_lshl_add_u64 v[40:41], v[36:37], 0, v[142:143]
	global_load_dwordx4 v[36:39], v[40:41], off
	global_load_dwordx4 v[176:179], v[40:41], off offset:64
	global_load_dwordx4 v[180:183], v[40:41], off offset:512
	global_load_dwordx4 v[184:187], v[40:41], off offset:576
	v_lshlrev_b64 v[42:43], 11, v[34:35]
	v_lshlrev_b64 v[44:45], 12, v[34:35]
	v_lshl_add_u64 v[42:43], s[10:11], 0, v[42:43]
	v_lshl_add_u64 v[44:45], s[86:87], 0, v[44:45]
	v_lshl_add_u64 v[44:45], v[44:45], 0, v[142:143]
	v_lshl_add_u64 v[42:43], v[138:139], 1, v[42:43]
	v_readlane_b32 s68, v239, 4
	v_readlane_b32 s69, v239, 5
	v_readlane_b32 s70, v239, 6
	v_readlane_b32 s71, v239, 7
	v_readlane_b32 s72, v239, 8
	v_readlane_b32 s73, v239, 9
	v_readlane_b32 s74, v239, 10
	v_readlane_b32 s75, v239, 11
	v_readlane_b32 s76, v239, 12
	v_readlane_b32 s77, v239, 13
	v_readlane_b32 s78, v239, 14
	v_readlane_b32 s79, v239, 15
	s_waitcnt vmcnt(0)
	v_pk_add_f32 v[30:31], v[30:31], v[36:37]
	v_pk_add_f32 v[32:33], v[32:33], v[38:39]
	v_cvt_pk_bf16_f32 v230, v30, v31
	v_cvt_pk_bf16_f32 v231, v32, v33
	global_store_dwordx4 v[44:45], v[30:33], off
	v_mul_f32_e32 v46, v33, v33
	v_pk_add_f32 v[26:27], v[26:27], v[176:177]
	v_pk_add_f32 v[28:29], v[28:29], v[178:179]
	v_cvt_pk_bf16_f32 v232, v26, v27
	v_cvt_pk_bf16_f32 v233, v28, v29
	global_store_dwordx4 v[44:45], v[26:29], off offset:64
	v_permlane16_swap_b32_e32 v230, v232
	v_permlane16_swap_b32_e32 v231, v233
	global_store_dwordx4 v[42:43], v[230:233], off
	v_pk_add_f32 v[22:23], v[22:23], v[180:181]
	v_pk_add_f32 v[24:25], v[24:25], v[182:183]
	v_cvt_pk_bf16_f32 v234, v22, v23
	v_cvt_pk_bf16_f32 v235, v24, v25
	global_store_dwordx4 v[44:45], v[22:25], off offset:512
	v_mul_f32_e32 v40, v31, v31
	v_pk_fma_f32 v[30:31], v[30:31], v[30:31], v[40:41] op_sel_hi:[1,1,0]
	v_mul_f32_e32 v40, v29, v29
	v_pk_fma_f32 v[30:31], v[32:33], v[32:33], v[30:31]
	v_mul_f32_e32 v32, v27, v27
	v_pk_fma_f32 v[26:27], v[26:27], v[26:27], v[32:33] op_sel_hi:[1,1,0]
	v_pk_add_f32 v[30:31], v[46:47], v[30:31] op_sel_hi:[0,1]
	v_pk_fma_f32 v[26:27], v[28:29], v[28:29], v[26:27]
	v_mul_f32_e32 v28, v23, v23
	v_pk_add_f32 v[26:27], v[40:41], v[26:27] op_sel_hi:[0,1]
	v_pk_fma_f32 v[22:23], v[22:23], v[22:23], v[28:29] op_sel_hi:[1,1,0]
	v_pk_add_f32 v[26:27], v[30:31], v[26:27]
	v_mul_f32_e32 v30, v25, v25
	v_pk_fma_f32 v[22:23], v[24:25], v[24:25], v[22:23]
	v_pk_add_f32 v[18:19], v[18:19], v[184:185]
	v_pk_add_f32 v[20:21], v[20:21], v[186:187]
	v_mul_f32_e32 v24, v19, v19
	v_pk_add_f32 v[22:23], v[30:31], v[22:23] op_sel_hi:[0,1]
	global_store_dwordx4 v[44:45], v[18:21], off offset:576
	v_cvt_pk_bf16_f32 v236, v18, v19
	v_pk_add_f32 v[22:23], v[26:27], v[22:23]
	v_pk_fma_f32 v[18:19], v[18:19], v[18:19], v[24:25] op_sel_hi:[1,1,0]
	v_mul_f32_e32 v26, v21, v21
	v_pk_fma_f32 v[18:19], v[20:21], v[20:21], v[18:19]
	v_cvt_pk_bf16_f32 v237, v20, v21
	v_pk_add_f32 v[18:19], v[26:27], v[18:19] op_sel_hi:[0,1]
	v_pk_add_f32 v[18:19], v[22:23], v[18:19]
	v_permlane16_swap_b32_e32 v234, v236
	v_permlane16_swap_b32_e32 v235, v237
	global_store_dwordx4 v[42:43], v[234:237], off offset:256
	v_mov_b32_e32 v19, v18
	s_nop 1
	v_permlane16_swap_b32_e32 v18, v19
	v_add_f32_e32 v18, v18, v19
	v_mov_b32_e32 v19, v18
	s_nop 1
	v_permlane32_swap_b32_e32 v18, v19
	s_and_saveexec_b64 s[24:25], s[4:5]
	s_cbranch_execz .LBB0_765
	v_add_f32_e32 v20, v18, v19
	v_lshl_add_u64 v[18:19], v[34:35], 2, s[12:13]
	global_atomic_add_f32 v[18:19], v20, off
;   __device__ __forceinline__ void operator()(const acc8_t& acc, const pg8::Unit& u, int wr, int wc, int fr, int fq) const {
;     ...
;     for (int ai = 0; ai < 2; ai++)
; #pragma unroll
;       for (int m = 0; m < 4; m++) {
;         const int token = (int)EPI_TOKEN(u, ai, m);
;         const float* xr = xrow(p, token);
;         float ss = 0.f;
; #pragma unroll
;         for (int bj = 0; bj < 2; bj++)
; #pragma unroll
;           for (int n = 0; n < 2; n++) {
;             const int f = EPI_COL(u, bj, n);
;             const float4 xv = *(const float4*)(xr + f);
;             const float4 o = make_float4(xv.x + acc[ai][bj][m][n][0], xv.y + acc[ai][bj][m][n][1], xv.z + acc[ai][bj][m][n][2], xv.w + acc[ai][bj][m][n][3]);
;             ss += o.x * o.x + o.y * o.y + o.z * o.z + o.w * o.w;
;             *(float4*)(p.out + O_Y + (size_t)token * 1024 + f) = o;
;             uint2 ob; ob.x = pack2(o.x, o.y); ob.y = pack2(o.z, o.w);
;             *(uint2*)(X1B + (size_t)token * 1024 + f) = ob;
;           }
;         ss = xsum16(ss);
;         ss = xsum32(ss);
;         if (fq == 0) atomicAdd(rss + token, ss);
.LBB0_765:
	s_or_b64 exec, exec, s[24:25]
	v_readlane_b32 s64, v239, 0
	v_readlane_b32 s65, v239, 1
	v_readlane_b32 s66, v239, 2
	v_readlane_b32 s67, v239, 3
	s_mov_b64 s[52:53], s[64:65]
	v_add_u32_e32 v18, 0xb0, v140
	s_mov_b64 s[54:55], s[66:67]
	v_ashrrev_i32_e32 v19, 31, v18
	v_add_u32_e32 v20, 0xffff80b0, v140
	v_cmp_gt_i32_e32 vcc, s57, v18
	v_mov_b32_e32 v22, s55
	v_mov_b32_e32 v23, s53
	v_cndmask_b32_e32 v21, 0, v19, vcc
	v_cndmask_b32_e32 v20, v20, v18, vcc
	v_cndmask_b32_e32 v23, v22, v23, vcc
	v_mov_b32_e32 v22, s54
	v_mov_b32_e32 v24, s52
	v_cndmask_b32_e32 v22, v22, v24, vcc
	v_lshlrev_b64 v[20:21], 12, v[20:21]
	v_lshl_add_u64 v[20:21], v[22:23], 0, v[20:21]
	v_lshl_add_u64 v[24:25], v[20:21], 0, v[142:143]
	global_load_dwordx4 v[20:23], v[24:25], off
	global_load_dwordx4 v[176:179], v[24:25], off offset:64
	global_load_dwordx4 v[180:183], v[24:25], off offset:512
	global_load_dwordx4 v[184:187], v[24:25], off offset:576
	v_lshlrev_b64 v[26:27], 11, v[18:19]
	v_lshlrev_b64 v[28:29], 12, v[18:19]
	v_lshl_add_u64 v[26:27], s[10:11], 0, v[26:27]
	v_lshl_add_u64 v[28:29], s[86:87], 0, v[28:29]
	v_lshl_add_u64 v[28:29], v[28:29], 0, v[142:143]
	v_lshl_add_u64 v[26:27], v[138:139], 1, v[26:27]
	v_readlane_b32 s68, v239, 4
	v_readlane_b32 s69, v239, 5
	v_readlane_b32 s70, v239, 6
	v_readlane_b32 s71, v239, 7
	v_readlane_b32 s72, v239, 8
	v_readlane_b32 s73, v239, 9
	v_readlane_b32 s74, v239, 10
	v_readlane_b32 s75, v239, 11
	v_readlane_b32 s76, v239, 12
	v_readlane_b32 s77, v239, 13
	v_readlane_b32 s78, v239, 14
	v_readlane_b32 s79, v239, 15
	s_waitcnt vmcnt(0)
	v_pk_add_f32 v[14:15], v[14:15], v[20:21]
	v_pk_add_f32 v[16:17], v[16:17], v[22:23]
	v_cvt_pk_bf16_f32 v230, v14, v15
	v_cvt_pk_bf16_f32 v231, v16, v17
	global_store_dwordx4 v[28:29], v[14:17], off
	v_mul_f32_e32 v30, v17, v17
	v_pk_add_f32 v[10:11], v[10:11], v[176:177]
	v_pk_add_f32 v[12:13], v[12:13], v[178:179]
	v_cvt_pk_bf16_f32 v232, v10, v11
	v_cvt_pk_bf16_f32 v233, v12, v13
	global_store_dwordx4 v[28:29], v[10:13], off offset:64
	v_permlane16_swap_b32_e32 v230, v232
	v_permlane16_swap_b32_e32 v231, v233
	global_store_dwordx4 v[26:27], v[230:233], off
	v_pk_add_f32 v[6:7], v[6:7], v[180:181]
	v_pk_add_f32 v[8:9], v[8:9], v[182:183]
	v_cvt_pk_bf16_f32 v234, v6, v7
	v_cvt_pk_bf16_f32 v235, v8, v9
	global_store_dwordx4 v[28:29], v[6:9], off offset:512
	v_mul_f32_e32 v24, v15, v15
	v_pk_fma_f32 v[14:15], v[14:15], v[14:15], v[24:25] op_sel_hi:[1,1,0]
	v_mul_f32_e32 v24, v13, v13
	v_pk_fma_f32 v[14:15], v[16:17], v[16:17], v[14:15]
	v_mul_f32_e32 v16, v11, v11
	v_pk_fma_f32 v[10:11], v[10:11], v[10:11], v[16:17] op_sel_hi:[1,1,0]
	v_pk_add_f32 v[14:15], v[30:31], v[14:15] op_sel_hi:[0,1]
	v_pk_fma_f32 v[10:11], v[12:13], v[12:13], v[10:11]
	v_mul_f32_e32 v12, v7, v7
	v_pk_add_f32 v[10:11], v[24:25], v[10:11] op_sel_hi:[0,1]
	v_pk_fma_f32 v[6:7], v[6:7], v[6:7], v[12:13] op_sel_hi:[1,1,0]
	v_pk_add_f32 v[10:11], v[14:15], v[10:11]
	v_mul_f32_e32 v14, v9, v9
	v_pk_fma_f32 v[6:7], v[8:9], v[8:9], v[6:7]
	v_pk_add_f32 v[2:3], v[2:3], v[184:185]
	v_pk_add_f32 v[4:5], v[4:5], v[186:187]
	v_mul_f32_e32 v8, v3, v3
	v_pk_add_f32 v[6:7], v[14:15], v[6:7] op_sel_hi:[0,1]
	global_store_dwordx4 v[28:29], v[2:5], off offset:576
	v_cvt_pk_bf16_f32 v236, v2, v3
	v_pk_add_f32 v[6:7], v[10:11], v[6:7]
	v_pk_fma_f32 v[2:3], v[2:3], v[2:3], v[8:9] op_sel_hi:[1,1,0]
	v_mul_f32_e32 v10, v5, v5
	v_pk_fma_f32 v[2:3], v[4:5], v[4:5], v[2:3]
	v_cvt_pk_bf16_f32 v237, v4, v5
	v_pk_add_f32 v[2:3], v[10:11], v[2:3] op_sel_hi:[0,1]
	v_pk_add_f32 v[2:3], v[6:7], v[2:3]
	v_permlane16_swap_b32_e32 v234, v236
	v_permlane16_swap_b32_e32 v235, v237
	global_store_dwordx4 v[26:27], v[234:237], off offset:256
	v_mov_b32_e32 v3, v2
	s_nop 1
	v_permlane16_swap_b32_e32 v2, v3
	v_add_f32_e32 v2, v2, v3
	v_mov_b32_e32 v3, v2
	s_nop 1
	v_permlane32_swap_b32_e32 v2, v3
	s_and_saveexec_b64 s[24:25], s[4:5]
	s_cbranch_execz .LBB0_743
	v_add_f32_e32 v4, v2, v3
	v_lshl_add_u64 v[2:3], v[18:19], 2, s[12:13]
	global_atomic_add_f32 v[2:3], v4, off
	s_branch .LBB0_743
